# v3 plus nt hints on streaming elementwise phases, per-unit vmcnt(0) drains removed in two GEMM instances, census loads de-serialized
# baseline (speedup 1.0000x reference)
; __device__ __forceinline__ unsigned xb_ld(unsigned* p)              { return __hip_atomic_load(p, __ATOMIC_RELAXED, __HIP_MEMORY_SCOPE_AGENT); }
; __device__ __forceinline__ void xcd_barrier_complete(unsigned* bar, unsigned x, unsigned& nloc, unsigned& nx) {
;     const unsigned G = gridDim.x * gridDim.y * gridDim.z;
;     unsigned sum, cnt, mine, sp = 0u;
;     for (;;) {
;         sum = 0u; cnt = 0u; mine = 0u;
; #pragma unroll
;         for (unsigned j = 0; j < 16; ++j) { const unsigned c = xb_ld(&bar[XB_XCNT(j)]); sum += c; cnt += (c > 0u) ? 1u : 0u; mine = (j == x) ? c : mine; }
;         if (sum == G) break;
;         __builtin_amdgcn_s_sleep(1);
;         if ((++sp & 255u) == 0u) { if (xb_ld(&bar[XB_TMO])) break; if (sp > XB_SPIN_CAP) { atomicAdd(&bar[XB_TMO], 1u); break; } }
;     }
;     nloc = mine > 0u ? mine : 1u; nx = cnt > 0u ? cnt : 1u;
.LBB0_193:
	v_readlane_b32 s6, v255, 16
	v_readlane_b32 s7, v255, 17
	s_mov_b64 s[8:9], -1
	s_waitcnt lgkmcnt(0)
	s_nop 2
	global_load_dword v0, v236, s[6:7] sc1
	v_readlane_b32 s6, v255, 18
	v_readlane_b32 s7, v255, 19
	s_nop 4
	global_load_dword v1, v236, s[6:7] sc1
	v_readlane_b32 s6, v255, 20
	v_readlane_b32 s7, v255, 21
	s_nop 4
	global_load_dword v2, v236, s[6:7] sc1
	v_readlane_b32 s6, v255, 22
	v_readlane_b32 s7, v255, 23
	s_nop 4
	global_load_dword v3, v236, s[6:7] sc1
	v_readlane_b32 s6, v255, 24
	v_readlane_b32 s7, v255, 25
	s_nop 4
	global_load_dword v4, v236, s[6:7] sc1
	v_readlane_b32 s6, v255, 26
	v_readlane_b32 s7, v255, 27
	s_nop 4
	global_load_dword v5, v236, s[6:7] sc1
	v_readlane_b32 s6, v255, 28
	v_readlane_b32 s7, v255, 29
	s_nop 4
	global_load_dword v6, v236, s[6:7] sc1
	v_readlane_b32 s6, v255, 30
	v_readlane_b32 s7, v255, 31
	s_nop 4
	global_load_dword v7, v236, s[6:7] sc1
	v_readlane_b32 s6, v255, 32
	v_readlane_b32 s7, v255, 33
	s_nop 4
	global_load_dword v8, v236, s[6:7] sc1
	v_readlane_b32 s6, v255, 34
	v_readlane_b32 s7, v255, 35
	s_nop 4
	global_load_dword v9, v236, s[6:7] sc1
	v_readlane_b32 s6, v255, 36
	v_readlane_b32 s7, v255, 37
	s_nop 4
	global_load_dword v10, v236, s[6:7] sc1
	v_readlane_b32 s6, v255, 38
	v_readlane_b32 s7, v255, 39
	s_nop 4
	global_load_dword v11, v236, s[6:7] sc1
	v_readlane_b32 s6, v255, 40
	v_readlane_b32 s7, v255, 41
	s_nop 4
	global_load_dword v12, v236, s[6:7] sc1
	v_readlane_b32 s6, v255, 42
	v_readlane_b32 s7, v255, 43
	s_nop 4
	global_load_dword v13, v236, s[6:7] sc1
	v_readlane_b32 s6, v255, 44
	v_readlane_b32 s7, v255, 45
	s_nop 4
	global_load_dword v14, v236, s[6:7] sc1
	v_readlane_b32 s6, v255, 46
	v_readlane_b32 s7, v255, 47
	s_nop 4
	global_load_dword v15, v236, s[6:7] sc1
	s_mov_b64 s[6:7], -1
	s_waitcnt vmcnt(0)
	v_add_u32_e32 v16, v1, v0
	v_add_u32_e32 v16, v16, v2
	v_add_u32_e32 v16, v16, v3
	v_add_u32_e32 v16, v16, v4
	v_add_u32_e32 v16, v16, v5
	v_add_u32_e32 v16, v16, v6
	v_add_u32_e32 v16, v16, v7
	v_add_u32_e32 v16, v16, v8
	v_add_u32_e32 v16, v16, v9
	v_add_u32_e32 v16, v16, v10
	v_add_u32_e32 v16, v16, v11
	v_add_u32_e32 v16, v16, v12
	v_add_u32_e32 v16, v16, v13
	v_add_u32_e32 v16, v16, v14
	v_add_u32_e32 v16, v16, v15
	v_cmp_eq_u32_e32 vcc, s27, v16
	s_cbranch_vccnz .LBB0_192
	s_and_b32 s6, s1, 0xff
	s_cmp_eq_u32 s6, 0
	s_mov_b64 s[6:7], -1
	s_mov_b64 s[10:11], -1
	s_sleep 1
	s_cbranch_scc0 .LBB0_197
	v_readlane_b32 s6, v255, 14
	v_readlane_b32 s7, v255, 15
	s_nop 4
	global_load_dword v16, v236, s[6:7] sc1
	s_waitcnt vmcnt(0)
	v_cmp_eq_u32_e32 vcc, 0, v16
	s_cbranch_vccnz .LBB0_199
	s_mov_b64 s[10:11], 0
	s_mov_b64 s[6:7], -1

; __device__ __forceinline__ f32x4 bf4(v2u u) { return (f32x4){bflo(u.x), bfhi(u.x), bflo(u.y), bfhi(u.y)}; }
; __device__ __forceinline__ float row16_sum(float x) { x += dpp_f<0xB1>(x); x += dpp_f<0x4E>(x); x += dpp_f<0x141>(x); x += dpp_f<0x140>(x); return x; }
; __device__ __forceinline__ void rw_post(const bf16* Y, bf16* R, const bf16* K, const bf16* V, const bf16* A, const bf16* G, const float* k_a, const float* r_k, const float* ln_g, const float* ln_b, int gw, int ngw, int lane) {
;     ...
;     for (int it = gw; it < M * 4; it += 2 * ngw) {
;         const int it2 = (it + ngw < M * 4) ? it + ngw : it;
;         const size_t off[2] = {(size_t)(it >> 2) * 1024 + c, (size_t)(it2 >> 2) * 1024 + c};
;         v2u yv[2], rv[2], kv[2], vv[2], av[2], gv[2];
; #pragma unroll
;         for (int u = 0; u < 2; ++u) { yv[u] = *(const v2u*)(Y + off[u]); rv[u] = *(const v2u*)(R + off[u]); kv[u] = *(const v2u*)(K + off[u]); vv[u] = *(const v2u*)(V + off[u]); av[u] = *(const v2u*)(A + off[u]); gv[u] = *(const v2u*)(G + off[u]); }
; #pragma unroll
;         for (int u = 0; u < 2; ++u) {
;             const f32x4 y = bf4(yv[u]), r = bf4(rv[u]), k = bf4(kv[u]), v = bf4(vv[u]), a = bf4(av[u]), g = bf4(gv[u]);
;             const float mu = row16_sum((y[0] + y[1]) + (y[2] + y[3])) * (1.0f / 64.0f);
;             const f32x4 yc = y - mu;
;             const float var = row16_sum((yc[0] * yc[0] + yc[1] * yc[1]) + (yc[2] * yc[2] + yc[3] * yc[3])) * (1.0f / 64.0f);
;             const float rstd = 1.0f / sqrtf(var + 64e-5f);
;             const f32x4 km = k * (1.0f + (a - 1.0f) * ka);
;             const f32x4 pr = r * km * rk;
;             const float cs = row16_sum((pr[0] + pr[1]) + (pr[2] + pr[3]));
;             const f32x4 o = (yc * rstd * lg + lb + v * cs) * g;
.LBB0_558:
	s_add_i32 s1, s16, s33
	s_cmp_lt_i32 s1, 0x20000
	s_cselect_b32 s17, s1, s16
	s_ashr_i32 s18, s16, 2
	s_ashr_i32 s19, s18, 31
	s_lshl_b64 s[18:19], s[18:19], 11
	v_or_b32_e32 v16, s18, v35
	v_mov_b32_e32 v17, s19
	v_lshl_add_u64 v[20:21], s[8:9], 0, v[16:17]
	s_waitcnt vmcnt(1)
	v_lshl_add_u64 v[18:19], s[10:11], 0, v[16:17]
	global_load_dwordx2 v[38:39], v[20:21], off nt
	global_load_dwordx2 v[40:41], v[18:19], off nt
	v_lshl_add_u64 v[18:19], s[6:7], 0, v[16:17]
	global_load_dwordx2 v[42:43], v[18:19], off nt
	v_lshl_add_u64 v[18:19], s[4:5], 0, v[16:17]
	global_load_dwordx2 v[44:45], v[18:19], off nt
	v_lshl_add_u64 v[18:19], s[12:13], 0, v[16:17]
	global_load_dwordx2 v[32:33], v[18:19], off nt
	s_ashr_i32 s18, s17, 2
	v_lshl_add_u64 v[16:17], s[14:15], 0, v[16:17]
	s_ashr_i32 s19, s18, 31
	global_load_dwordx2 v[36:37], v[16:17], off nt
	s_lshl_b64 s[18:19], s[18:19], 11
	v_or_b32_e32 v18, s18, v35
	v_mov_b32_e32 v19, s19
	v_lshl_add_u64 v[22:23], s[4:5], 0, v[18:19]
	v_lshl_add_u64 v[16:17], s[8:9], 0, v[18:19]
	v_lshl_add_u64 v[26:27], s[10:11], 0, v[18:19]
	v_lshl_add_u64 v[46:47], s[12:13], 0, v[18:19]
	v_lshl_add_u64 v[48:49], s[6:7], 0, v[18:19]
	v_lshl_add_u64 v[18:19], s[14:15], 0, v[18:19]
	global_load_dwordx2 v[24:25], v[22:23], off nt
	global_load_dwordx2 v[30:31], v[16:17], off nt
	global_load_dwordx2 v[28:29], v[26:27], off nt
	s_nop 0
	global_load_dwordx2 v[22:23], v[46:47], off nt
	global_load_dwordx2 v[26:27], v[48:49], off nt
	s_nop 0
	global_load_dwordx2 v[18:19], v[18:19], off nt
	s_cmp_eq_u32 s16, s17
	s_waitcnt vmcnt(11)
	v_lshlrev_b32_e32 v46, 16, v38
	s_waitcnt vmcnt(10)
	v_lshlrev_b32_e32 v48, 16, v40
	v_and_b32_e32 v49, 0xffff0000, v40
	s_waitcnt vmcnt(9)
	v_lshlrev_b32_e32 v50, 16, v42
	v_and_b32_e32 v51, 0xffff0000, v42
	s_waitcnt vmcnt(8)
	v_lshlrev_b32_e32 v53, 16, v45
	v_lshlrev_b32_e32 v52, 16, v44
	v_and_b32_e32 v45, 0xffff0000, v45
	v_and_b32_e32 v44, 0xffff0000, v44
	v_lshlrev_b32_e32 v42, 16, v43
	v_and_b32_e32 v43, 0xffff0000, v43
	v_pk_add_f32 v[56:57], v[52:53], v[44:45]
	s_waitcnt vmcnt(7)
	v_lshlrev_b32_e32 v54, 16, v32
	v_and_b32_e32 v55, 0xffff0000, v32
	v_pk_add_f32 v[42:43], v[42:43], -1.0 op_sel_hi:[1,0]
	v_pk_add_f32 v[50:51], v[50:51], -1.0 op_sel_hi:[1,0]
	v_add_f32_e32 v32, v56, v57
	v_lshlrev_b32_e32 v40, 16, v41
	v_and_b32_e32 v41, 0xffff0000, v41
	v_pk_fma_f32 v[50:51], v[0:1], v[50:51], 1.0 op_sel_hi:[1,1,0]
	v_pk_fma_f32 v[42:43], v[2:3], v[42:43], 1.0 op_sel_hi:[1,1,0]
	v_add_f32_dpp v32, v32, v32 quad_perm:[1,0,3,2] row_mask:0xf bank_mask:0xf bound_ctrl:1
	v_and_b32_e32 v47, 0xffff0000, v38
	v_lshlrev_b32_e32 v38, 16, v39
	v_and_b32_e32 v39, 0xffff0000, v39
	v_pk_mul_f32 v[40:41], v[42:43], v[40:41]
	v_pk_mul_f32 v[42:43], v[50:51], v[48:49]
	v_add_f32_dpp v32, v32, v32 quad_perm:[2,3,0,1] row_mask:0xf bank_mask:0xf bound_ctrl:1
	v_pk_mul_f32 v[42:43], v[42:43], v[46:47]
	v_pk_mul_f32 v[38:39], v[40:41], v[38:39]
	v_add_f32_dpp v32, v32, v32 row_half_mirror row_mask:0xf bank_mask:0xf bound_ctrl:1
	v_pk_mul_f32 v[38:39], v[6:7], v[38:39]
	v_pk_mul_f32 v[40:41], v[4:5], v[42:43]
	v_add_f32_dpp v32, v32, v32 row_mirror row_mask:0xf bank_mask:0xf bound_ctrl:1
	v_pk_mov_b32 v[42:43], v[40:41], v[38:39] op_sel:[1,0]
	v_mov_b32_e32 v41, v39
	v_fmac_f32_e32 v44, 0xbc800000, v32
	v_fmac_f32_e32 v45, 0xbc800000, v32
	v_fmac_f32_e32 v53, 0xbc800000, v32
	v_fmac_f32_e32 v52, 0xbc800000, v32
	v_pk_add_f32 v[38:39], v[42:43], v[40:41]
	v_mov_b32_e32 v40, v53
	v_mov_b32_e32 v41, v45
	v_mov_b32_e32 v53, v44
	v_add_f32_e32 v32, v38, v39
	v_pk_mul_f32 v[38:39], v[40:41], v[40:41]
	v_pk_mul_f32 v[42:43], v[52:53], v[52:53]
	v_add_f32_dpp v32, v32, v32 quad_perm:[1,0,3,2] row_mask:0xf bank_mask:0xf bound_ctrl:1
	v_pk_mov_b32 v[44:45], v[42:43], v[38:39] op_sel:[1,0]
	v_mov_b32_e32 v43, v39
	v_pk_add_f32 v[38:39], v[44:45], v[42:43]
	v_add_f32_dpp v32, v32, v32 quad_perm:[2,3,0,1] row_mask:0xf bank_mask:0xf bound_ctrl:1
	v_add_f32_e32 v34, v38, v39
	s_nop 0
	v_add_f32_dpp v32, v32, v32 row_half_mirror row_mask:0xf bank_mask:0xf bound_ctrl:1
	v_add_f32_dpp v34, v34, v34 quad_perm:[1,0,3,2] row_mask:0xf bank_mask:0xf bound_ctrl:1
	s_nop 0
	v_mov_b32_dpp v39, v32 row_mirror row_mask:0xf bank_mask:0xf bound_ctrl:1
	v_add_f32_dpp v34, v34, v34 quad_perm:[2,3,0,1] row_mask:0xf bank_mask:0xf bound_ctrl:1
	v_add_f32_e32 v32, v32, v39
	s_nop 0
	v_add_f32_dpp v34, v34, v34 row_half_mirror row_mask:0xf bank_mask:0xf bound_ctrl:1
	s_nop 1
	v_mov_b32_dpp v38, v34 row_mirror row_mask:0xf bank_mask:0xf bound_ctrl:1
	v_add_f32_e32 v34, v34, v38
	v_mov_b32_e32 v38, 0x3a27c5ac
	v_fmamk_f32 v34, v34, 0x3c800000, v38
	v_mul_f32_e32 v38, 0x4f800000, v34
	v_cmp_gt_f32_e32 vcc, s24, v34
	s_nop 1
	v_cndmask_b32_e32 v34, v34, v38, vcc
	v_sqrt_f32_e32 v38, v34
	s_nop 0
	v_add_u32_e32 v42, -1, v38
	v_add_u32_e32 v43, 1, v38
	v_fma_f32 v44, -v42, v38, v34
	v_fma_f32 v45, -v43, v38, v34
	v_cmp_ge_f32_e64 s[38:39], 0, v44
	s_nop 1
	v_cndmask_b32_e64 v38, v38, v42, s[38:39]
	v_cmp_lt_f32_e64 s[38:39], 0, v45
	s_nop 1
	v_cndmask_b32_e64 v38, v38, v43, s[38:39]
	v_mul_f32_e32 v42, 0x37800000, v38
	v_cndmask_b32_e32 v38, v38, v42, vcc
	v_cmp_class_f32_e32 vcc, v34, v229
	s_nop 1
	v_cndmask_b32_e32 v34, v38, v34, vcc
	v_div_scale_f32 v38, s[16:17], v34, v34, 1.0
	v_rcp_f32_e32 v42, v38
	v_div_scale_f32 v39, vcc, 1.0, v34, 1.0
	v_fma_f32 v43, -v38, v42, 1.0
	v_fmac_f32_e32 v42, v43, v42
	v_mul_f32_e32 v43, v39, v42
	v_fma_f32 v44, -v38, v43, v39
	v_fmac_f32_e32 v43, v44, v42
	v_fma_f32 v38, -v38, v43, v39
	v_div_fmas_f32 v38, v38, v42, v43
	v_div_fixup_f32 v34, v38, v34, 1.0
	v_pk_mul_f32 v[38:39], v[52:53], v[34:35] op_sel_hi:[1,0]
	v_pk_mul_f32 v[40:41], v[40:41], v[34:35] op_sel_hi:[1,0]
	v_pk_fma_f32 v[38:39], v[8:9], v[38:39], v[12:13]
	v_pk_fma_f32 v[40:41], v[10:11], v[40:41], v[14:15]
	v_lshlrev_b32_e32 v42, 16, v33
	v_and_b32_e32 v43, 0xffff0000, v33
	v_pk_fma_f32 v[38:39], v[32:33], v[54:55], v[38:39] op_sel_hi:[0,1,1]
	v_pk_fma_f32 v[32:33], v[32:33], v[42:43], v[40:41] op_sel_hi:[0,1,1]
	s_waitcnt vmcnt(6)
; __device__ __forceinline__ unsigned pk2(float lo, float hi) { const f32x2_t v = {lo, hi}; const bf16x2_t b = __builtin_convertvector(v, bf16x2_t); return __builtin_bit_cast(unsigned, b); }
; __device__ __forceinline__ f32x4 bf4(v2u u) { return (f32x4){bflo(u.x), bfhi(u.x), bflo(u.y), bfhi(u.y)}; }
; __device__ __forceinline__ float row16_sum(float x) { x += dpp_f<0xB1>(x); x += dpp_f<0x4E>(x); x += dpp_f<0x141>(x); x += dpp_f<0x140>(x); return x; }
; __device__ __forceinline__ void rw_post(const bf16* Y, bf16* R, const bf16* K, const bf16* V, const bf16* A, const bf16* G, const float* k_a, const float* r_k, const float* ln_g, const float* ln_b, int gw, int ngw, int lane) {
;     ...
;         for (int u = 0; u < 2; ++u) {
;             const f32x4 y = bf4(yv[u]), r = bf4(rv[u]), k = bf4(kv[u]), v = bf4(vv[u]), a = bf4(av[u]), g = bf4(gv[u]);
;             const float mu = row16_sum((y[0] + y[1]) + (y[2] + y[3])) * (1.0f / 64.0f);
;             const f32x4 yc = y - mu;
;             const float var = row16_sum((yc[0] * yc[0] + yc[1] * yc[1]) + (yc[2] * yc[2] + yc[3] * yc[3])) * (1.0f / 64.0f);
;             const float rstd = 1.0f / sqrtf(var + 64e-5f);
;             const f32x4 km = k * (1.0f + (a - 1.0f) * ka);
;             const f32x4 pr = r * km * rk;
;             const float cs = row16_sum((pr[0] + pr[1]) + (pr[2] + pr[3]));
;             const f32x4 o = (yc * rstd * lg + lb + v * cs) * g;
;             v2u wv; wv.x = pk2(o[0], o[1]); wv.y = pk2(o[2], o[3]);
;             if (u == 0 || it2 != it) *(v2u*)(R + off[u]) = wv;
	v_lshlrev_b32_e32 v40, 16, v36
	v_and_b32_e32 v41, 0xffff0000, v36
	v_lshlrev_b32_e32 v36, 16, v37
	v_and_b32_e32 v37, 0xffff0000, v37
	v_pk_mul_f32 v[32:33], v[32:33], v[36:37]
	v_pk_mul_f32 v[36:37], v[38:39], v[40:41]
	s_waitcnt vmcnt(1)
	v_lshlrev_b32_e32 v40, 16, v26
	v_cvt_pk_bf16_f32 v36, v36, v37
	v_cvt_pk_bf16_f32 v37, v32, v33
	global_store_dwordx2 v[20:21], v[36:37], off nt
	v_and_b32_e32 v41, 0xffff0000, v26
	v_lshlrev_b32_e32 v42, 16, v27
	v_and_b32_e32 v43, 0xffff0000, v27
	v_lshlrev_b32_e32 v27, 16, v25
	v_lshlrev_b32_e32 v26, 16, v24
	v_and_b32_e32 v21, 0xffff0000, v25
	v_and_b32_e32 v20, 0xffff0000, v24
	v_pk_add_f32 v[24:25], v[26:27], v[20:21]
	v_lshlrev_b32_e32 v36, 16, v28
	v_add_f32_e32 v24, v24, v25
	v_and_b32_e32 v37, 0xffff0000, v28
	v_pk_add_f32 v[40:41], v[40:41], -1.0 op_sel_hi:[1,0]
	v_add_f32_dpp v24, v24, v24 quad_perm:[1,0,3,2] row_mask:0xf bank_mask:0xf bound_ctrl:1
	v_lshlrev_b32_e32 v38, 16, v29
	v_and_b32_e32 v39, 0xffff0000, v29
	v_add_f32_dpp v24, v24, v24 quad_perm:[2,3,0,1] row_mask:0xf bank_mask:0xf bound_ctrl:1
	v_pk_fma_f32 v[40:41], v[0:1], v[40:41], 1.0 op_sel_hi:[1,1,0]
	v_lshlrev_b32_e32 v32, 16, v30
	v_add_f32_dpp v24, v24, v24 row_half_mirror row_mask:0xf bank_mask:0xf bound_ctrl:1
	v_and_b32_e32 v33, 0xffff0000, v30
	v_lshlrev_b32_e32 v30, 16, v31
	v_add_f32_dpp v24, v24, v24 row_mirror row_mask:0xf bank_mask:0xf bound_ctrl:1
	v_fmac_f32_e32 v21, 0xbc800000, v24
	v_fmac_f32_e32 v20, 0xbc800000, v24
	v_fmac_f32_e32 v27, 0xbc800000, v24
	v_fmac_f32_e32 v26, 0xbc800000, v24
	v_mul_f32_e32 v24, v20, v20
	v_mul_f32_e32 v25, v21, v21
	v_fmac_f32_e32 v24, v26, v26
	v_fmac_f32_e32 v25, v27, v27
	v_add_f32_e32 v24, v24, v25
	v_and_b32_e32 v31, 0xffff0000, v31
	v_pk_mul_f32 v[36:37], v[40:41], v[36:37]
	v_add_f32_dpp v24, v24, v24 quad_perm:[1,0,3,2] row_mask:0xf bank_mask:0xf bound_ctrl:1
	v_pk_mul_f32 v[32:33], v[36:37], v[32:33]
	s_nop 0
	v_add_f32_dpp v24, v24, v24 quad_perm:[2,3,0,1] row_mask:0xf bank_mask:0xf bound_ctrl:1
	s_nop 1
	v_add_f32_dpp v28, v24, v24 row_half_mirror row_mask:0xf bank_mask:0xf bound_ctrl:1
	v_pk_add_f32 v[24:25], v[42:43], -1.0 op_sel_hi:[1,0]
	s_nop 0
	v_pk_fma_f32 v[24:25], v[2:3], v[24:25], 1.0 op_sel_hi:[1,1,0]
	v_mov_b32_dpp v29, v28 row_mirror row_mask:0xf bank_mask:0xf bound_ctrl:1
	v_pk_mul_f32 v[24:25], v[24:25], v[38:39]
	s_nop 0
	v_pk_mul_f32 v[24:25], v[24:25], v[30:31]
	v_pk_mul_f32 v[30:31], v[4:5], v[32:33]
	v_pk_mul_f32 v[24:25], v[6:7], v[24:25]
	v_add_f32_e32 v30, v30, v31
	v_add_f32_e32 v24, v24, v25
	v_add_f32_e32 v24, v30, v24
	s_nop 1
	v_add_f32_dpp v24, v24, v24 quad_perm:[1,0,3,2] row_mask:0xf bank_mask:0xf bound_ctrl:1
	s_nop 1
	v_add_f32_dpp v24, v24, v24 quad_perm:[2,3,0,1] row_mask:0xf bank_mask:0xf bound_ctrl:1
	s_nop 1
	v_add_f32_dpp v24, v24, v24 row_half_mirror row_mask:0xf bank_mask:0xf bound_ctrl:1
	s_nop 1
	v_mov_b32_dpp v25, v24 row_mirror row_mask:0xf bank_mask:0xf bound_ctrl:1
	s_cbranch_scc1 .LBB0_557
	v_add_f32_e32 v28, v28, v29
	v_mov_b32_e32 v29, 0x3a27c5ac
	v_fmamk_f32 v28, v28, 0x3c800000, v29
	v_mul_f32_e32 v29, 0x4f800000, v28
	v_cmp_gt_f32_e32 vcc, s24, v28
	v_add_f32_e32 v24, v24, v25
	s_nop 0
	v_cndmask_b32_e32 v28, v28, v29, vcc
	v_sqrt_f32_e32 v29, v28
	s_nop 0
	v_add_u32_e32 v30, -1, v29
	v_fma_f32 v32, -v30, v29, v28
	v_add_u32_e32 v31, 1, v29
	v_cmp_ge_f32_e64 s[38:39], 0, v32
	s_nop 1
	v_cndmask_b32_e64 v30, v29, v30, s[38:39]
	v_fma_f32 v29, -v31, v29, v28
	v_cmp_lt_f32_e64 s[38:39], 0, v29
	s_nop 1
	v_cndmask_b32_e64 v29, v30, v31, s[38:39]
	v_mul_f32_e32 v30, 0x37800000, v29
	v_cndmask_b32_e32 v29, v29, v30, vcc
	v_cmp_class_f32_e32 vcc, v28, v229
	s_nop 1
	v_cndmask_b32_e32 v30, v29, v28, vcc
	v_div_scale_f32 v31, s[16:17], v30, v30, 1.0
	v_rcp_f32_e32 v32, v31
	v_mov_b32_e32 v29, v20
	v_mov_b32_e32 v28, v26
	v_fma_f32 v20, -v31, v32, 1.0
	v_fmac_f32_e32 v32, v20, v32
	v_div_scale_f32 v20, vcc, 1.0, v30, 1.0
	v_mul_f32_e32 v26, v20, v32
	v_fma_f32 v33, -v31, v26, v20
	v_fmac_f32_e32 v26, v33, v32
	v_fma_f32 v20, -v31, v26, v20
	v_div_fmas_f32 v20, v20, v32, v26
	v_div_fixup_f32 v26, v20, v30, 1.0
	v_mov_b32_e32 v20, v27
	v_pk_mul_f32 v[28:29], v[28:29], v[26:27] op_sel_hi:[1,0]
	v_pk_mul_f32 v[20:21], v[20:21], v[26:27] op_sel_hi:[1,0]
	v_pk_fma_f32 v[26:27], v[8:9], v[28:29], v[12:13]
	v_pk_fma_f32 v[20:21], v[10:11], v[20:21], v[14:15]
	v_lshlrev_b32_e32 v28, 16, v22
	v_and_b32_e32 v29, 0xffff0000, v22
	v_lshlrev_b32_e32 v22, 16, v23
	v_and_b32_e32 v23, 0xffff0000, v23
	v_pk_fma_f32 v[26:27], v[24:25], v[28:29], v[26:27] op_sel_hi:[0,1,1]
	v_pk_fma_f32 v[20:21], v[24:25], v[22:23], v[20:21] op_sel_hi:[0,1,1]
	s_waitcnt vmcnt(1)
	v_lshlrev_b32_e32 v22, 16, v18
	v_and_b32_e32 v23, 0xffff0000, v18
	v_lshlrev_b32_e32 v18, 16, v19
	v_and_b32_e32 v19, 0xffff0000, v19
	v_pk_mul_f32 v[18:19], v[20:21], v[18:19]
	v_pk_mul_f32 v[20:21], v[26:27], v[22:23]
	s_nop 0
	v_cvt_pk_bf16_f32 v20, v20, v21
	v_cvt_pk_bf16_f32 v21, v18, v19
	global_store_dwordx2 v[16:17], v[20:21], off nt
	s_branch .LBB0_557

; #define PG8_STAGE(bufoff, gbase, voff) do { _Pragma("unroll") for (int _i = 0; _i < 2; ++_i) \
;         __builtin_amdgcn_global_load_lds((const unsigned*)((const char*)(gbase) + (voff)[_i]), (PG8_LAS unsigned*)(lds + (bufoff) + ldsw + _i * 8192), 16, 0, 0); } while (0)
; #define PG8_LDA(dst, b, h) do { _Pragma("unroll") for (int m = 0; m < 4; ++m) _Pragma("unroll") for (int k = 0; k < 2; ++k) dst[m][k] = *(const PG8_LAS bf16x8*)(lds + PG8_SA(b, h) + aoff + m * 2048 + k * 1024); } while (0)
; #define PG8_LDB(dst, b, h) do { _Pragma("unroll") for (int n = 0; n < 2; ++n) _Pragma("unroll") for (int k = 0; k < 2; ++k) dst[n][k] = *(const PG8_LAS bf16x8*)(lds + PG8_SB(b, h) + boff + n * 2048 + k * 1024); } while (0)
; #define PG8_WAIT_V(n) asm volatile("s_waitcnt vmcnt(" #n ")" ::: "memory")
; #define PG8_WAIT_L(n) asm volatile("s_waitcnt lgkmcnt(" #n ")" ::: "memory")
; #define PG8_BAR __builtin_amdgcn_s_barrier()
; #define PG8_SCHED __builtin_amdgcn_sched_barrier(0)
; template <class Epi, class Sched, bool ALIGN_EPI = false, bool SP2 = false>
; __device__ __forceinline__ void gemm_phase(PG8_LAS unsigned char* lds, const Gemm g, const Sched& S, const Epi& E) {
;     ...
;         const char* nA = has_next ? (const char*)g.A + (size_t)nxt.pm * tstep : cA; const char* nB = has_next ? (const char*)g.Bt + (size_t)nxt.pn * tstep : cB;
;         for (int t = 0; t < nt; t += 2) {
;             const bool last = (t == nt - 2);
;             const char* a1 = cA + (size_t)(t + 1) * kstep;
;             const char* a2 = last ? nA : cA + (size_t)(t + 2) * kstep; const char* b2 = last ? nB : cB + (size_t)(t + 2) * kstep;
;             const char* a3 = a2 + kstep; const char* b3 = b2 + kstep;
;             if (last && has_next) S.a_ready(nxt);
;             if constexpr (SP2) {
;             PG8_LDB(B0, 0, 0); PG8_LDB(B1, 0, 1); PG8_SCHED; PG8_LDA(At, 0, 0); PG8_STAGE(PG8_SA(1, 1), a1 + hstep, voffA);
;             PG8_WAIT_V(8); PG8_WAIT_L(0); PG8_BAR; PG8_MMA(0, 0, At, B0); PG8_MMA(0, 1, At, B1); PG8_BAR; PG8_SCHED;
;     ...
; #pragma unroll
;         for (int a = 0; a < 2; ++a)
; #pragma unroll
;             for (int b = 0; b < 2; ++b)
; #pragma unroll
;                 for (int m = 0; m < 4; ++m)
; #pragma unroll
;                     for (int n = 0; n < 2; ++n) acc[a][b][m][n] = (f32x4){0.f, 0.f, 0.f, 0.f};
;         cur = nxt; cA = nA; cB = nB; ++ui;
.LBB0_573:
	s_ashr_i32 s53, s52, 31
	s_lshl_b64 s[8:9], s[52:53], 19
	s_add_u32 s54, s12, s8
	s_addc_u32 s55, s13, s9
	s_and_b64 s[8:9], s[38:39], exec
	s_cselect_b32 s41, s55, s5
	s_cselect_b32 s53, s54, s4
	s_ashr_i32 s49, s48, 31
	s_lshl_b64 s[8:9], s[48:49], 19
	s_add_u32 s56, s10, s8
	s_addc_u32 s57, s11, s9
	s_and_b64 s[8:9], s[38:39], exec
	s_cselect_b32 s49, s57, s7
	s_cselect_b32 s58, s56, s6
	s_add_u32 s4, s4, 0x40080
	s_addc_u32 s5, s5, 0
	s_add_u32 s59, s6, 0x100
	v_mov_b32_e32 v0, 0
	s_addc_u32 s64, s7, 0
	s_mov_b32 s65, -2
	v_mov_b32_e32 v1, v0
	v_mov_b32_e32 v2, v0
	v_mov_b32_e32 v3, v0
	v_mov_b32_e32 v4, v0
	v_mov_b32_e32 v5, v0
	v_mov_b32_e32 v6, v0
	v_mov_b32_e32 v7, v0
	v_mov_b32_e32 v28, v0
	v_mov_b32_e32 v29, v0
	v_mov_b32_e32 v30, v0
	v_mov_b32_e32 v31, v0
	v_mov_b32_e32 v40, v0
	v_mov_b32_e32 v41, v0
	v_mov_b32_e32 v42, v0
	v_mov_b32_e32 v43, v0
	v_mov_b32_e32 v52, v0
	v_mov_b32_e32 v53, v0
	v_mov_b32_e32 v54, v0
	v_mov_b32_e32 v55, v0
	v_mov_b32_e32 v56, v0
	v_mov_b32_e32 v57, v0
	v_mov_b32_e32 v58, v0
	v_mov_b32_e32 v59, v0
	v_mov_b32_e32 v68, v0
	v_mov_b32_e32 v69, v0
	v_mov_b32_e32 v70, v0
	v_mov_b32_e32 v71, v0
	v_mov_b32_e32 v72, v0
	v_mov_b32_e32 v73, v0
	v_mov_b32_e32 v74, v0
	v_mov_b32_e32 v75, v0
	v_mov_b32_e32 v12, v0
	v_mov_b32_e32 v13, v0
	v_mov_b32_e32 v14, v0
	v_mov_b32_e32 v15, v0
	v_mov_b32_e32 v20, v0
	v_mov_b32_e32 v21, v0
	v_mov_b32_e32 v22, v0
	v_mov_b32_e32 v23, v0
	v_mov_b32_e32 v44, v0
	v_mov_b32_e32 v45, v0
	v_mov_b32_e32 v46, v0
	v_mov_b32_e32 v47, v0
	v_mov_b32_e32 v48, v0
	v_mov_b32_e32 v49, v0
	v_mov_b32_e32 v50, v0
	v_mov_b32_e32 v51, v0
	v_mov_b32_e32 v60, v0
	v_mov_b32_e32 v61, v0
	v_mov_b32_e32 v62, v0
	v_mov_b32_e32 v63, v0
	v_mov_b32_e32 v64, v0
	v_mov_b32_e32 v65, v0
	v_mov_b32_e32 v66, v0
	v_mov_b32_e32 v67, v0
	v_mov_b32_e32 v76, v0
	v_mov_b32_e32 v77, v0
	v_mov_b32_e32 v78, v0
	v_mov_b32_e32 v79, v0
	v_mov_b32_e32 v80, v0
	v_mov_b32_e32 v81, v0
	v_mov_b32_e32 v82, v0
	v_mov_b32_e32 v83, v0
	v_mov_b32_e32 v84, v0
	v_mov_b32_e32 v85, v0
	v_mov_b32_e32 v86, v0
	v_mov_b32_e32 v87, v0
	v_mov_b32_e32 v88, v0
	v_mov_b32_e32 v89, v0
	v_mov_b32_e32 v90, v0
	v_mov_b32_e32 v91, v0
	v_mov_b32_e32 v100, v0
	v_mov_b32_e32 v101, v0
	v_mov_b32_e32 v102, v0
	v_mov_b32_e32 v103, v0
	v_mov_b32_e32 v104, v0
	v_mov_b32_e32 v105, v0
	v_mov_b32_e32 v106, v0
	v_mov_b32_e32 v107, v0
	v_mov_b32_e32 v116, v0
	v_mov_b32_e32 v117, v0
	v_mov_b32_e32 v118, v0
	v_mov_b32_e32 v119, v0
	v_mov_b32_e32 v120, v0
	v_mov_b32_e32 v121, v0
	v_mov_b32_e32 v122, v0
	v_mov_b32_e32 v123, v0
	v_mov_b32_e32 v132, v0
	v_mov_b32_e32 v133, v0
	v_mov_b32_e32 v134, v0
	v_mov_b32_e32 v135, v0
	v_mov_b32_e32 v136, v0
	v_mov_b32_e32 v137, v0
	v_mov_b32_e32 v138, v0
	v_mov_b32_e32 v139, v0
	v_mov_b32_e32 v92, v0
	v_mov_b32_e32 v93, v0
	v_mov_b32_e32 v94, v0
	v_mov_b32_e32 v95, v0
	v_mov_b32_e32 v96, v0
	v_mov_b32_e32 v97, v0
	v_mov_b32_e32 v98, v0
	v_mov_b32_e32 v99, v0
	v_mov_b32_e32 v108, v0
	v_mov_b32_e32 v109, v0
	v_mov_b32_e32 v110, v0
	v_mov_b32_e32 v111, v0
	v_mov_b32_e32 v112, v0
	v_mov_b32_e32 v113, v0
	v_mov_b32_e32 v114, v0
	v_mov_b32_e32 v115, v0
	v_mov_b32_e32 v124, v0
	v_mov_b32_e32 v125, v0
	v_mov_b32_e32 v126, v0
	v_mov_b32_e32 v127, v0
	v_mov_b32_e32 v128, v0
	v_mov_b32_e32 v129, v0
	v_mov_b32_e32 v130, v0
	v_mov_b32_e32 v131, v0
	v_mov_b32_e32 v140, v0
	v_mov_b32_e32 v141, v0
	v_mov_b32_e32 v142, v0
	v_mov_b32_e32 v143, v0
	v_mov_b32_e32 v144, v0
	v_mov_b32_e32 v145, v0
	v_mov_b32_e32 v146, v0
	v_mov_b32_e32 v147, v0
.LBB0_574:
	s_add_u32 s6, s4, 0xfffc0080
	s_addc_u32 s7, s5, -1
	s_add_i32 s68, 0, 0x10000
	s_cmp_eq_u32 s65, 12
	s_cselect_b32 s9, s41, s7
	s_cselect_b32 s8, s53, s6
	v_add_u32_e32 v34, s68, v198
	s_cselect_b32 s7, s49, s64
	s_cselect_b32 s6, s58, s59
	s_add_i32 s72, 0, 0x14000
	ds_read_b128 v[8:11], v34
	ds_read_b128 v[16:19], v34 offset:1024
	ds_read_b128 v[24:27], v34 offset:2048
	ds_read_b128 v[36:39], v34 offset:3072
	v_add_u32_e32 v34, s72, v198
	ds_read_b128 v[160:163], v34
	ds_read_b128 v[180:183], v34 offset:1024
	ds_read_b128 v[184:187], v34 offset:2048
	ds_read_b128 v[188:191], v34 offset:3072
	v_lshl_add_u64 v[164:165], s[4:5], 0, v[156:157]
	s_add_i32 m0, s15, 0xc000
	ds_read_b128 v[192:195], v200
	ds_read_b128 v[202:205], v200 offset:1024
	ds_read_b128 v[206:209], v200 offset:2048
	ds_read_b128 v[210:213], v200 offset:3072
	ds_read_b128 v[214:217], v200 offset:4096
	ds_read_b128 v[218:221], v200 offset:5120
	ds_read_b128 v[222:225], v200 offset:6144
	ds_read_b128 v[240:243], v200 offset:7168
	global_load_lds_dwordx4 v[164:165], off
	v_lshl_add_u64 v[164:165], s[4:5], 0, v[158:159]
	s_add_i32 m0, s15, 0xe000
	s_nop 0
	global_load_lds_dwordx4 v[164:165], off
	s_waitcnt vmcnt(8)
	s_waitcnt lgkmcnt(0)
	s_barrier
; #define PG8_STAGE(bufoff, gbase, voff) do { _Pragma("unroll") for (int _i = 0; _i < 2; ++_i) \
;         __builtin_amdgcn_global_load_lds((const unsigned*)((const char*)(gbase) + (voff)[_i]), (PG8_LAS unsigned*)(lds + (bufoff) + ldsw + _i * 8192), 16, 0, 0); } while (0)
; #define PG8_LDA(dst, b, h) do { _Pragma("unroll") for (int m = 0; m < 4; ++m) _Pragma("unroll") for (int k = 0; k < 2; ++k) dst[m][k] = *(const PG8_LAS bf16x8*)(lds + PG8_SA(b, h) + aoff + m * 2048 + k * 1024); } while (0)
; #define PG8_MMA(ai, bj, At, Bt) do { __builtin_amdgcn_s_setprio(1); _Pragma("unroll") for (int m = 0; m < 4; ++m) _Pragma("unroll") for (int n = 0; n < 2; ++n) _Pragma("unroll") for (int k = 0; k < 2; ++k) \
;         acc[ai][bj][m][n] = __builtin_amdgcn_mfma_f32_16x16x32_bf16(Bt[n][k], At[m][k], acc[ai][bj][m][n], 0, 0, 0); __builtin_amdgcn_s_setprio(0); } while (0)
; #define PG8_WAIT_V(n) asm volatile("s_waitcnt vmcnt(" #n ")" ::: "memory")
; #define PG8_WAIT_L(n) asm volatile("s_waitcnt lgkmcnt(" #n ")" ::: "memory")
; #define PG8_BAR __builtin_amdgcn_s_barrier()
; #define PG8_SCHED __builtin_amdgcn_sched_barrier(0)
; template <class Epi, class Sched, bool ALIGN_EPI = false, bool SP2 = false>
; __device__ __forceinline__ void gemm_phase(PG8_LAS unsigned char* lds, const Gemm g, const Sched& S, const Epi& E) {
;     ...
;             PG8_WAIT_V(8); PG8_WAIT_L(0); PG8_BAR; PG8_MMA(0, 0, At, B0); PG8_MMA(0, 1, At, B1); PG8_BAR; PG8_SCHED;
;             PG8_LDA(At, 0, 1); PG8_STAGE(PG8_SB(0, 0), b2, voffB); PG8_STAGE(PG8_SB(0, 1), b2 + hstep, voffB); PG8_STAGE(PG8_SA(0, 0), a2, voffA);
;             PG8_WAIT_V(8); PG8_WAIT_L(0); PG8_BAR; PG8_MMA(1, 0, At, B0); PG8_MMA(1, 1, At, B1); PG8_BAR; PG8_SCHED;
	s_setprio 1
	s_waitcnt lgkmcnt(0)
	v_mfma_f32_16x16x32_bf16 v[144:147], v[8:11], v[192:195], v[144:147]
	v_mfma_f32_16x16x32_bf16 v[140:143], v[24:27], v[192:195], v[140:143]
	v_mfma_f32_16x16x32_bf16 v[128:131], v[8:11], v[206:209], v[128:131]
	v_mfma_f32_16x16x32_bf16 v[124:127], v[24:27], v[206:209], v[124:127]
	v_mfma_f32_16x16x32_bf16 v[112:115], v[8:11], v[214:217], v[112:115]
	v_mfma_f32_16x16x32_bf16 v[108:111], v[24:27], v[214:217], v[108:111]
	v_mfma_f32_16x16x32_bf16 v[96:99], v[8:11], v[222:225], v[96:99]
	v_mfma_f32_16x16x32_bf16 v[92:95], v[24:27], v[222:225], v[92:95]
	v_mfma_f32_16x16x32_bf16 v[144:147], v[16:19], v[202:205], v[144:147]
	v_mfma_f32_16x16x32_bf16 v[140:143], v[36:39], v[202:205], v[140:143]
	v_mfma_f32_16x16x32_bf16 v[128:131], v[16:19], v[210:213], v[128:131]
	v_mfma_f32_16x16x32_bf16 v[124:127], v[36:39], v[210:213], v[124:127]
	v_mfma_f32_16x16x32_bf16 v[112:115], v[16:19], v[218:221], v[112:115]
	v_mfma_f32_16x16x32_bf16 v[108:111], v[36:39], v[218:221], v[108:111]
	v_mfma_f32_16x16x32_bf16 v[96:99], v[16:19], v[240:243], v[96:99]
	v_mfma_f32_16x16x32_bf16 v[92:95], v[36:39], v[240:243], v[92:95]
	s_setprio 0
	s_setprio 1
	v_mfma_f32_16x16x32_bf16 v[136:139], v[160:163], v[192:195], v[136:139]
	v_mfma_f32_16x16x32_bf16 v[132:135], v[184:187], v[192:195], v[132:135]
	v_mfma_f32_16x16x32_bf16 v[120:123], v[160:163], v[206:209], v[120:123]
	v_mfma_f32_16x16x32_bf16 v[116:119], v[184:187], v[206:209], v[116:119]
	v_mfma_f32_16x16x32_bf16 v[104:107], v[160:163], v[214:217], v[104:107]
	v_mfma_f32_16x16x32_bf16 v[100:103], v[184:187], v[214:217], v[100:103]
	v_mfma_f32_16x16x32_bf16 v[88:91], v[160:163], v[222:225], v[88:91]
	v_mfma_f32_16x16x32_bf16 v[84:87], v[184:187], v[222:225], v[84:87]
	v_mfma_f32_16x16x32_bf16 v[136:139], v[180:183], v[202:205], v[136:139]
	v_mfma_f32_16x16x32_bf16 v[132:135], v[188:191], v[202:205], v[132:135]
	v_mfma_f32_16x16x32_bf16 v[120:123], v[180:183], v[210:213], v[120:123]
	v_mfma_f32_16x16x32_bf16 v[116:119], v[188:191], v[210:213], v[116:119]
	v_mfma_f32_16x16x32_bf16 v[104:107], v[180:183], v[218:221], v[104:107]
	v_mfma_f32_16x16x32_bf16 v[100:103], v[188:191], v[218:221], v[100:103]
	v_mfma_f32_16x16x32_bf16 v[88:91], v[180:183], v[240:243], v[88:91]
	v_mfma_f32_16x16x32_bf16 v[84:87], v[188:191], v[240:243], v[84:87]
	s_setprio 0
	s_barrier
	s_add_i32 s68, s68, s14
	v_lshl_add_u64 v[164:165], s[6:7], 0, v[150:151]
	s_mov_b32 m0, s68
	ds_read_b128 v[192:195], v200 offset:16384
	ds_read_b128 v[202:205], v200 offset:17408
	ds_read_b128 v[206:209], v200 offset:18432
	ds_read_b128 v[210:213], v200 offset:19456
	ds_read_b128 v[214:217], v200 offset:20480
	ds_read_b128 v[218:221], v200 offset:21504
	ds_read_b128 v[222:225], v200 offset:22528
	ds_read_b128 v[240:243], v200 offset:23552
	global_load_lds_dwordx4 v[164:165], off
	s_add_i32 m0, s68, 0x2000
	s_add_u32 s68, s6, 0x40000
	v_lshl_add_u64 v[166:167], s[6:7], 0, v[32:33]
	s_addc_u32 s69, s7, 0
	s_add_i32 s72, s72, s14
	global_load_lds_dwordx4 v[166:167], off
	v_lshl_add_u64 v[168:169], s[68:69], 0, v[150:151]
	s_mov_b32 m0, s72
	v_lshl_add_u64 v[170:171], s[8:9], 0, v[148:149]
	global_load_lds_dwordx4 v[168:169], off
	v_lshl_add_u64 v[168:169], s[68:69], 0, v[32:33]
	s_add_i32 m0, s72, 0x2000
	s_nop 0
	global_load_lds_dwordx4 v[168:169], off
	v_lshl_add_u64 v[168:169], s[8:9], 0, v[152:153]
	s_mov_b32 m0, s15
	s_nop 0
	global_load_lds_dwordx4 v[168:169], off
	s_mov_b32 m0, s16
	s_nop 0
	global_load_lds_dwordx4 v[170:171], off
	s_waitcnt vmcnt(8)
	s_waitcnt lgkmcnt(0)
	s_barrier
	s_setprio 1
	s_waitcnt lgkmcnt(0)
	v_mfma_f32_16x16x32_bf16 v[80:83], v[8:11], v[192:195], v[80:83]
	v_mfma_f32_16x16x32_bf16 v[76:79], v[24:27], v[192:195], v[76:79]
	v_mfma_f32_16x16x32_bf16 v[64:67], v[8:11], v[206:209], v[64:67]
	v_mfma_f32_16x16x32_bf16 v[60:63], v[24:27], v[206:209], v[60:63]
	v_mfma_f32_16x16x32_bf16 v[48:51], v[8:11], v[214:217], v[48:51]
	v_mfma_f32_16x16x32_bf16 v[44:47], v[24:27], v[214:217], v[44:47]
	v_mfma_f32_16x16x32_bf16 v[12:15], v[24:27], v[222:225], v[12:15]
	v_mfma_f32_16x16x32_bf16 v[80:83], v[16:19], v[202:205], v[80:83]
	v_mfma_f32_16x16x32_bf16 v[76:79], v[36:39], v[202:205], v[76:79]
	v_mfma_f32_16x16x32_bf16 v[64:67], v[16:19], v[210:213], v[64:67]
	v_mfma_f32_16x16x32_bf16 v[60:63], v[36:39], v[210:213], v[60:63]
	v_mfma_f32_16x16x32_bf16 v[48:51], v[16:19], v[218:221], v[48:51]
	v_mfma_f32_16x16x32_bf16 v[44:47], v[36:39], v[218:221], v[44:47]
	v_mfma_f32_16x16x32_bf16 v[8:11], v[8:11], v[222:225], v[20:23]
	v_mfma_f32_16x16x32_bf16 v[12:15], v[36:39], v[240:243], v[12:15]
	v_mfma_f32_16x16x32_bf16 v[8:11], v[16:19], v[240:243], v[8:11]
	s_setprio 0
	s_setprio 1
	v_mfma_f32_16x16x32_bf16 v[20:23], v[184:187], v[192:195], v[68:71]
	v_mfma_f32_16x16x32_bf16 v[24:27], v[188:191], v[202:205], v[20:23]
	v_mfma_f32_16x16x32_bf16 v[20:23], v[160:163], v[206:209], v[56:59]
	v_mfma_f32_16x16x32_bf16 v[36:39], v[180:183], v[210:213], v[20:23]
	v_mfma_f32_16x16x32_bf16 v[20:23], v[184:187], v[206:209], v[52:55]
	v_mfma_f32_16x16x32_bf16 v[52:55], v[188:191], v[210:213], v[20:23]
	v_mfma_f32_16x16x32_bf16 v[20:23], v[160:163], v[214:217], v[40:43]
	v_mfma_f32_16x16x32_bf16 v[40:43], v[180:183], v[218:221], v[20:23]
	v_mfma_f32_16x16x32_bf16 v[20:23], v[184:187], v[214:217], v[28:31]
	v_mfma_f32_16x16x32_bf16 v[4:7], v[160:163], v[222:225], v[4:7]
	v_mfma_f32_16x16x32_bf16 v[0:3], v[184:187], v[222:225], v[0:3]
	v_mfma_f32_16x16x32_bf16 v[16:19], v[160:163], v[192:195], v[72:75]
	v_mfma_f32_16x16x32_bf16 v[28:31], v[188:191], v[218:221], v[20:23]
	v_mfma_f32_16x16x32_bf16 v[4:7], v[180:183], v[240:243], v[4:7]
	v_mfma_f32_16x16x32_bf16 v[0:3], v[188:191], v[240:243], v[0:3]
	v_mfma_f32_16x16x32_bf16 v[16:19], v[180:183], v[202:205], v[16:19]
	s_setprio 0
	s_barrier
; #define PG8_STAGE(bufoff, gbase, voff) do { _Pragma("unroll") for (int _i = 0; _i < 2; ++_i) \
;         __builtin_amdgcn_global_load_lds((const unsigned*)((const char*)(gbase) + (voff)[_i]), (PG8_LAS unsigned*)(lds + (bufoff) + ldsw + _i * 8192), 16, 0, 0); } while (0)
; #define PG8_LDA(dst, b, h) do { _Pragma("unroll") for (int m = 0; m < 4; ++m) _Pragma("unroll") for (int k = 0; k < 2; ++k) dst[m][k] = *(const PG8_LAS bf16x8*)(lds + PG8_SA(b, h) + aoff + m * 2048 + k * 1024); } while (0)
; #define PG8_LDB(dst, b, h) do { _Pragma("unroll") for (int n = 0; n < 2; ++n) _Pragma("unroll") for (int k = 0; k < 2; ++k) dst[n][k] = *(const PG8_LAS bf16x8*)(lds + PG8_SB(b, h) + boff + n * 2048 + k * 1024); } while (0)
; #define PG8_MMA(ai, bj, At, Bt) do { __builtin_amdgcn_s_setprio(1); _Pragma("unroll") for (int m = 0; m < 4; ++m) _Pragma("unroll") for (int n = 0; n < 2; ++n) _Pragma("unroll") for (int k = 0; k < 2; ++k) \
;         acc[ai][bj][m][n] = __builtin_amdgcn_mfma_f32_16x16x32_bf16(Bt[n][k], At[m][k], acc[ai][bj][m][n], 0, 0, 0); __builtin_amdgcn_s_setprio(0); } while (0)
; #define PG8_WAIT_V(n) asm volatile("s_waitcnt vmcnt(" #n ")" ::: "memory")
; #define PG8_WAIT_L(n) asm volatile("s_waitcnt lgkmcnt(" #n ")" ::: "memory")
; #define PG8_BAR __builtin_amdgcn_s_barrier()
; #define PG8_SCHED __builtin_amdgcn_sched_barrier(0)
; template <class Epi, class Sched, bool ALIGN_EPI = false, bool SP2 = false>
; __device__ __forceinline__ void gemm_phase(PG8_LAS unsigned char* lds, const Gemm g, const Sched& S, const Epi& E) {
;     ...
;             PG8_LDB(B0, 1, 0); PG8_LDB(B1, 1, 1); PG8_SCHED; PG8_LDA(At, 1, 0); PG8_STAGE(PG8_SA(0, 1), a2 + hstep, voffA);
;             PG8_WAIT_V(8); PG8_WAIT_L(0); PG8_BAR; PG8_MMA(0, 0, At, B0); PG8_MMA(0, 1, At, B1); PG8_BAR; PG8_SCHED;
	s_add_i32 s68, 0, 0x18000
	v_add_u32_e32 v34, s68, v198
	s_add_i32 s69, 0, 0x1c000
	ds_read_b128 v[20:23], v34
	ds_read_b128 v[56:59], v34 offset:1024
	ds_read_b128 v[68:71], v34 offset:2048
	ds_read_b128 v[72:75], v34 offset:3072
	v_add_u32_e32 v34, s69, v198
	ds_read_b128 v[160:163], v34
	ds_read_b128 v[180:183], v34 offset:1024
	ds_read_b128 v[184:187], v34 offset:2048
	ds_read_b128 v[188:191], v34 offset:3072
	s_add_u32 s8, s8, 0x40000
	s_addc_u32 s9, s9, 0
	s_mov_b32 m0, s17
	v_lshl_add_u64 v[172:173], s[8:9], 0, v[152:153]
	ds_read_b128 v[192:195], v200 offset:32768
	ds_read_b128 v[202:205], v200 offset:33792
	ds_read_b128 v[206:209], v200 offset:34816
	ds_read_b128 v[210:213], v200 offset:35840
	ds_read_b128 v[214:217], v200 offset:36864
	ds_read_b128 v[218:221], v200 offset:37888
	ds_read_b128 v[222:225], v200 offset:38912
	ds_read_b128 v[240:243], v200 offset:39936
	global_load_lds_dwordx4 v[172:173], off
	v_lshl_add_u64 v[172:173], s[8:9], 0, v[148:149]
	s_mov_b32 m0, s18
	s_nop 0
	global_load_lds_dwordx4 v[172:173], off
	s_waitcnt vmcnt(8)
	s_waitcnt lgkmcnt(0)
	s_barrier
	s_setprio 1
	s_waitcnt lgkmcnt(0)
	v_mfma_f32_16x16x32_bf16 v[144:147], v[20:23], v[192:195], v[144:147]
	v_mfma_f32_16x16x32_bf16 v[140:143], v[68:71], v[192:195], v[140:143]
	v_mfma_f32_16x16x32_bf16 v[128:131], v[20:23], v[206:209], v[128:131]
	v_mfma_f32_16x16x32_bf16 v[124:127], v[68:71], v[206:209], v[124:127]
	v_mfma_f32_16x16x32_bf16 v[112:115], v[20:23], v[214:217], v[112:115]
	v_mfma_f32_16x16x32_bf16 v[108:111], v[68:71], v[214:217], v[108:111]
	v_mfma_f32_16x16x32_bf16 v[96:99], v[20:23], v[222:225], v[96:99]
	v_mfma_f32_16x16x32_bf16 v[92:95], v[68:71], v[222:225], v[92:95]
	v_mfma_f32_16x16x32_bf16 v[144:147], v[56:59], v[202:205], v[144:147]
	v_mfma_f32_16x16x32_bf16 v[140:143], v[72:75], v[202:205], v[140:143]
	v_mfma_f32_16x16x32_bf16 v[128:131], v[56:59], v[210:213], v[128:131]
	v_mfma_f32_16x16x32_bf16 v[124:127], v[72:75], v[210:213], v[124:127]
	v_mfma_f32_16x16x32_bf16 v[112:115], v[56:59], v[218:221], v[112:115]
	v_mfma_f32_16x16x32_bf16 v[108:111], v[72:75], v[218:221], v[108:111]
	v_mfma_f32_16x16x32_bf16 v[96:99], v[56:59], v[240:243], v[96:99]
	v_mfma_f32_16x16x32_bf16 v[92:95], v[72:75], v[240:243], v[92:95]
	s_setprio 0
	s_setprio 1
	v_mfma_f32_16x16x32_bf16 v[136:139], v[160:163], v[192:195], v[136:139]
	v_mfma_f32_16x16x32_bf16 v[132:135], v[184:187], v[192:195], v[132:135]
	v_mfma_f32_16x16x32_bf16 v[120:123], v[160:163], v[206:209], v[120:123]
	v_mfma_f32_16x16x32_bf16 v[116:119], v[184:187], v[206:209], v[116:119]
	v_mfma_f32_16x16x32_bf16 v[104:107], v[160:163], v[214:217], v[104:107]
	v_mfma_f32_16x16x32_bf16 v[100:103], v[184:187], v[214:217], v[100:103]
	v_mfma_f32_16x16x32_bf16 v[88:91], v[160:163], v[222:225], v[88:91]
	v_mfma_f32_16x16x32_bf16 v[84:87], v[184:187], v[222:225], v[84:87]
	v_mfma_f32_16x16x32_bf16 v[136:139], v[180:183], v[202:205], v[136:139]
	v_mfma_f32_16x16x32_bf16 v[132:135], v[188:191], v[202:205], v[132:135]
	v_mfma_f32_16x16x32_bf16 v[120:123], v[180:183], v[210:213], v[120:123]
	v_mfma_f32_16x16x32_bf16 v[116:119], v[188:191], v[210:213], v[116:119]
	v_mfma_f32_16x16x32_bf16 v[104:107], v[180:183], v[218:221], v[104:107]
	v_mfma_f32_16x16x32_bf16 v[100:103], v[188:191], v[218:221], v[100:103]
	v_mfma_f32_16x16x32_bf16 v[88:91], v[180:183], v[240:243], v[88:91]
	v_mfma_f32_16x16x32_bf16 v[84:87], v[188:191], v[240:243], v[84:87]
	s_setprio 0
	s_barrier
; #define PG8_STAGE(bufoff, gbase, voff) do { _Pragma("unroll") for (int _i = 0; _i < 2; ++_i) \
;         __builtin_amdgcn_global_load_lds((const unsigned*)((const char*)(gbase) + (voff)[_i]), (PG8_LAS unsigned*)(lds + (bufoff) + ldsw + _i * 8192), 16, 0, 0); } while (0)
; #define PG8_LDA(dst, b, h) do { _Pragma("unroll") for (int m = 0; m < 4; ++m) _Pragma("unroll") for (int k = 0; k < 2; ++k) dst[m][k] = *(const PG8_LAS bf16x8*)(lds + PG8_SA(b, h) + aoff + m * 2048 + k * 1024); } while (0)
; #define PG8_MMA(ai, bj, At, Bt) do { __builtin_amdgcn_s_setprio(1); _Pragma("unroll") for (int m = 0; m < 4; ++m) _Pragma("unroll") for (int n = 0; n < 2; ++n) _Pragma("unroll") for (int k = 0; k < 2; ++k) \
;         acc[ai][bj][m][n] = __builtin_amdgcn_mfma_f32_16x16x32_bf16(Bt[n][k], At[m][k], acc[ai][bj][m][n], 0, 0, 0); __builtin_amdgcn_s_setprio(0); } while (0)
; #define PG8_WAIT_V(n) asm volatile("s_waitcnt vmcnt(" #n ")" ::: "memory")
; #define PG8_WAIT_L(n) asm volatile("s_waitcnt lgkmcnt(" #n ")" ::: "memory")
; #define PG8_BAR __builtin_amdgcn_s_barrier()
; #define PG8_SCHED __builtin_amdgcn_sched_barrier(0)
; template <class Epi, class Sched, bool ALIGN_EPI = false, bool SP2 = false>
; __device__ __forceinline__ void gemm_phase(PG8_LAS unsigned char* lds, const Gemm g, const Sched& S, const Epi& E) {
;     ...
;         for (int t = 0; t < nt; t += 2) {
;     ...
;             PG8_LDA(At, 1, 1); PG8_STAGE(PG8_SB(1, 0), b3, voffB); PG8_STAGE(PG8_SB(1, 1), b3 + hstep, voffB); PG8_STAGE(PG8_SA(1, 0), a3, voffA);
;             PG8_WAIT_V(8); PG8_WAIT_L(0); PG8_BAR; PG8_MMA(1, 0, At, B0); PG8_MMA(1, 1, At, B1); PG8_BAR; PG8_SCHED;
	s_add_i32 s8, s68, s14
	v_lshl_add_u64 v[164:165], v[164:165], 0, s[66:67]
	s_mov_b32 m0, s8
	ds_read_b128 v[192:195], v200 offset:49152
	ds_read_b128 v[202:205], v200 offset:50176
	ds_read_b128 v[206:209], v200 offset:51200
	ds_read_b128 v[210:213], v200 offset:52224
	ds_read_b128 v[214:217], v200 offset:53248
	ds_read_b128 v[218:221], v200 offset:54272
	ds_read_b128 v[222:225], v200 offset:55296
	ds_read_b128 v[240:243], v200 offset:56320
	global_load_lds_dwordx4 v[164:165], off
	s_add_i32 m0, s8, 0x2000
	s_add_u32 s6, s6, 0x40080
	v_lshl_add_u64 v[164:165], v[166:167], 0, s[66:67]
	s_addc_u32 s7, s7, 0
	s_add_i32 s8, s69, s14
	global_load_lds_dwordx4 v[164:165], off
	v_lshl_add_u64 v[164:165], s[6:7], 0, v[150:151]
	s_mov_b32 m0, s8
	s_nop 0
	global_load_lds_dwordx4 v[164:165], off
	v_lshl_add_u64 v[164:165], s[6:7], 0, v[32:33]
	s_add_i32 m0, s8, 0x2000
	s_nop 0
	global_load_lds_dwordx4 v[164:165], off
	v_lshl_add_u64 v[164:165], v[168:169], 0, s[66:67]
	s_mov_b32 m0, s61
	s_nop 0
	global_load_lds_dwordx4 v[164:165], off
	v_lshl_add_u64 v[164:165], v[170:171], 0, s[66:67]
	s_mov_b32 m0, s62
	s_nop 0
	global_load_lds_dwordx4 v[164:165], off
	s_waitcnt vmcnt(8)
	s_waitcnt lgkmcnt(0)
	s_barrier
	s_setprio 1
	s_waitcnt lgkmcnt(0)
	v_mfma_f32_16x16x32_bf16 v[8:11], v[20:23], v[222:225], v[8:11]
	v_mfma_f32_16x16x32_bf16 v[80:83], v[20:23], v[192:195], v[80:83]
	v_mfma_f32_16x16x32_bf16 v[76:79], v[68:71], v[192:195], v[76:79]
	v_mfma_f32_16x16x32_bf16 v[64:67], v[20:23], v[206:209], v[64:67]
	v_mfma_f32_16x16x32_bf16 v[60:63], v[68:71], v[206:209], v[60:63]
	v_mfma_f32_16x16x32_bf16 v[48:51], v[20:23], v[214:217], v[48:51]
	v_mfma_f32_16x16x32_bf16 v[44:47], v[68:71], v[214:217], v[44:47]
	v_mfma_f32_16x16x32_bf16 v[20:23], v[56:59], v[240:243], v[8:11]
	v_mfma_f32_16x16x32_bf16 v[8:11], v[68:71], v[222:225], v[12:15]
	v_mfma_f32_16x16x32_bf16 v[80:83], v[56:59], v[202:205], v[80:83]
	v_mfma_f32_16x16x32_bf16 v[76:79], v[72:75], v[202:205], v[76:79]
	v_mfma_f32_16x16x32_bf16 v[64:67], v[56:59], v[210:213], v[64:67]
	v_mfma_f32_16x16x32_bf16 v[60:63], v[72:75], v[210:213], v[60:63]
	v_mfma_f32_16x16x32_bf16 v[48:51], v[56:59], v[218:221], v[48:51]
	v_mfma_f32_16x16x32_bf16 v[44:47], v[72:75], v[218:221], v[44:47]
	v_mfma_f32_16x16x32_bf16 v[12:15], v[72:75], v[240:243], v[8:11]
	s_setprio 0
	s_setprio 1
	v_mfma_f32_16x16x32_bf16 v[8:11], v[160:163], v[192:195], v[16:19]
	v_mfma_f32_16x16x32_bf16 v[72:75], v[180:183], v[202:205], v[8:11]
	v_mfma_f32_16x16x32_bf16 v[8:11], v[184:187], v[192:195], v[24:27]
	v_mfma_f32_16x16x32_bf16 v[68:71], v[188:191], v[202:205], v[8:11]
	v_mfma_f32_16x16x32_bf16 v[8:11], v[160:163], v[206:209], v[36:39]
	v_mfma_f32_16x16x32_bf16 v[56:59], v[180:183], v[210:213], v[8:11]
	v_mfma_f32_16x16x32_bf16 v[8:11], v[184:187], v[206:209], v[52:55]
	v_mfma_f32_16x16x32_bf16 v[52:55], v[188:191], v[210:213], v[8:11]
	v_mfma_f32_16x16x32_bf16 v[8:11], v[160:163], v[214:217], v[40:43]
	v_mfma_f32_16x16x32_bf16 v[40:43], v[180:183], v[218:221], v[8:11]
	v_mfma_f32_16x16x32_bf16 v[8:11], v[184:187], v[214:217], v[28:31]
	v_mfma_f32_16x16x32_bf16 v[4:7], v[160:163], v[222:225], v[4:7]
	v_mfma_f32_16x16x32_bf16 v[0:3], v[184:187], v[222:225], v[0:3]
	v_mfma_f32_16x16x32_bf16 v[28:31], v[188:191], v[218:221], v[8:11]
	v_mfma_f32_16x16x32_bf16 v[4:7], v[180:183], v[240:243], v[4:7]
	v_mfma_f32_16x16x32_bf16 v[0:3], v[188:191], v[240:243], v[0:3]
	s_setprio 0
	s_barrier
	s_add_i32 s65, s65, 2
	s_add_u32 s4, s4, 0x100
	s_addc_u32 s5, s5, 0
	s_add_u32 s59, s59, 0x100
	s_addc_u32 s64, s64, 0
	s_cmp_gt_u32 s65, 13
	s_cbranch_scc0 .LBB0_574
	s_and_b64 vcc, exec, s[46:47]
	s_cbranch_vccz .LBB0_577
	s_barrier

; template <class Epi, class Sched, bool ALIGN_EPI = false, bool SP2 = false>
; __device__ __forceinline__ void gemm_phase(PG8_LAS unsigned char* lds, const Gemm g, const Sched& S, const Epi& E) {
;     ...
;         const char* nA = has_next ? (const char*)g.A + (size_t)nxt.pm * tstep : cA; const char* nB = has_next ? (const char*)g.Bt + (size_t)nxt.pn * tstep : cB;
;     ...
; #pragma unroll
;         for (int a = 0; a < 2; ++a)
; #pragma unroll
;             for (int b = 0; b < 2; ++b)
; #pragma unroll
;                 for (int m = 0; m < 4; ++m)
; #pragma unroll
;                     for (int n = 0; n < 2; ++n) acc[a][b][m][n] = (f32x4){0.f, 0.f, 0.f, 0.f};
;         cur = nxt; cA = nA; cB = nB; ++ui;
.LBB0_2153:
	s_ashr_i32 s49, s48, 31
	s_lshl_b64 s[8:9], s[48:49], 19
	s_add_u32 s50, s12, s8
	s_addc_u32 s51, s13, s9
	s_and_b64 s[8:9], s[38:39], exec
	s_cselect_b32 s41, s51, s5
	s_cselect_b32 s49, s50, s4
	s_ashr_i32 s47, s46, 31
	s_lshl_b64 s[8:9], s[46:47], 19
	s_add_u32 s52, s10, s8
	s_addc_u32 s53, s11, s9
	s_and_b64 s[8:9], s[38:39], exec
	s_cselect_b32 s47, s53, s7
	s_cselect_b32 s58, s52, s6
	s_add_u32 s4, s4, 0x40080
	s_addc_u32 s5, s5, 0
	s_add_u32 s59, s6, 0x100
	v_mov_b32_e32 v0, 0
	s_addc_u32 s60, s7, 0
	s_mov_b32 s61, -2
	v_mov_b32_e32 v1, v0
	v_mov_b32_e32 v2, v0
	v_mov_b32_e32 v3, v0
	v_mov_b32_e32 v4, v0
	v_mov_b32_e32 v5, v0
	v_mov_b32_e32 v6, v0
	v_mov_b32_e32 v7, v0
	v_mov_b32_e32 v12, v0
	v_mov_b32_e32 v13, v0
	v_mov_b32_e32 v14, v0
	v_mov_b32_e32 v15, v0
	v_mov_b32_e32 v20, v0
	v_mov_b32_e32 v21, v0
	v_mov_b32_e32 v22, v0
	v_mov_b32_e32 v23, v0
	v_mov_b32_e32 v28, v0
	v_mov_b32_e32 v29, v0
	v_mov_b32_e32 v30, v0
	v_mov_b32_e32 v31, v0
	v_mov_b32_e32 v40, v0
	v_mov_b32_e32 v41, v0
	v_mov_b32_e32 v42, v0
	v_mov_b32_e32 v43, v0
	v_mov_b32_e32 v48, v0
	v_mov_b32_e32 v49, v0
	v_mov_b32_e32 v50, v0
	v_mov_b32_e32 v51, v0
	v_mov_b32_e32 v56, v0
	v_mov_b32_e32 v57, v0
	v_mov_b32_e32 v58, v0
	v_mov_b32_e32 v59, v0
	v_mov_b32_e32 v8, v0
	v_mov_b32_e32 v9, v0
	v_mov_b32_e32 v10, v0
	v_mov_b32_e32 v11, v0
	v_mov_b32_e32 v16, v0
	v_mov_b32_e32 v17, v0
	v_mov_b32_e32 v18, v0
	v_mov_b32_e32 v19, v0
	v_mov_b32_e32 v24, v0
	v_mov_b32_e32 v25, v0
	v_mov_b32_e32 v26, v0
	v_mov_b32_e32 v27, v0
	v_mov_b32_e32 v36, v0
	v_mov_b32_e32 v37, v0
	v_mov_b32_e32 v38, v0
	v_mov_b32_e32 v39, v0
	v_mov_b32_e32 v44, v0
	v_mov_b32_e32 v45, v0
	v_mov_b32_e32 v46, v0
	v_mov_b32_e32 v47, v0
	v_mov_b32_e32 v52, v0
	v_mov_b32_e32 v53, v0
	v_mov_b32_e32 v54, v0
	v_mov_b32_e32 v55, v0
	v_mov_b32_e32 v60, v0
	v_mov_b32_e32 v61, v0
	v_mov_b32_e32 v62, v0
	v_mov_b32_e32 v63, v0
	v_mov_b32_e32 v64, v0
	v_mov_b32_e32 v65, v0
	v_mov_b32_e32 v66, v0
	v_mov_b32_e32 v67, v0
	v_mov_b32_e32 v68, v0
	v_mov_b32_e32 v69, v0
	v_mov_b32_e32 v70, v0
	v_mov_b32_e32 v71, v0
	v_mov_b32_e32 v72, v0
	v_mov_b32_e32 v73, v0
	v_mov_b32_e32 v74, v0
	v_mov_b32_e32 v75, v0
	v_mov_b32_e32 v80, v0
	v_mov_b32_e32 v81, v0
	v_mov_b32_e32 v82, v0
	v_mov_b32_e32 v83, v0
	v_mov_b32_e32 v88, v0
	v_mov_b32_e32 v89, v0
	v_mov_b32_e32 v90, v0
	v_mov_b32_e32 v91, v0
	v_mov_b32_e32 v96, v0
	v_mov_b32_e32 v97, v0
	v_mov_b32_e32 v98, v0
	v_mov_b32_e32 v99, v0
	v_mov_b32_e32 v104, v0
	v_mov_b32_e32 v105, v0
	v_mov_b32_e32 v106, v0
	v_mov_b32_e32 v107, v0
	v_mov_b32_e32 v112, v0
	v_mov_b32_e32 v113, v0
	v_mov_b32_e32 v114, v0
	v_mov_b32_e32 v115, v0
	v_mov_b32_e32 v120, v0
	v_mov_b32_e32 v121, v0
	v_mov_b32_e32 v122, v0
	v_mov_b32_e32 v123, v0
	v_mov_b32_e32 v76, v0
	v_mov_b32_e32 v77, v0
	v_mov_b32_e32 v78, v0
	v_mov_b32_e32 v79, v0
	v_mov_b32_e32 v84, v0
	v_mov_b32_e32 v85, v0
	v_mov_b32_e32 v86, v0
	v_mov_b32_e32 v87, v0
	v_mov_b32_e32 v92, v0
	v_mov_b32_e32 v93, v0
	v_mov_b32_e32 v94, v0
	v_mov_b32_e32 v95, v0
	v_mov_b32_e32 v100, v0
	v_mov_b32_e32 v101, v0
	v_mov_b32_e32 v102, v0
	v_mov_b32_e32 v103, v0
	v_mov_b32_e32 v108, v0
	v_mov_b32_e32 v109, v0
	v_mov_b32_e32 v110, v0
	v_mov_b32_e32 v111, v0
	v_mov_b32_e32 v116, v0
	v_mov_b32_e32 v117, v0
	v_mov_b32_e32 v118, v0
	v_mov_b32_e32 v119, v0
	v_mov_b32_e32 v124, v0
	v_mov_b32_e32 v125, v0
	v_mov_b32_e32 v126, v0
	v_mov_b32_e32 v127, v0
	v_mov_b32_e32 v128, v0
	v_mov_b32_e32 v129, v0
	v_mov_b32_e32 v130, v0
	v_mov_b32_e32 v131, v0

; __device__ __forceinline__ unsigned pk2(float lo, float hi) { const f32x2_t v = {lo, hi}; const bf16x2_t b = __builtin_convertvector(v, bf16x2_t); return __builtin_bit_cast(unsigned, b); }
; __device__ __forceinline__ void sc_conv(const bf16* BG, const bf16* CG, const bf16* HX, const float* cw, const float* cb, bf16* O3, int gt, int ngt) {
;     ...
;     for (int idx = gt; idx < M * 128; idx += 2 * ngt) {
;         const int idx2 = idx + ngt < M * 128 ? idx + ngt : idx;
;         v4u cv[2][3], hv[2][3], bv[2]; int tt[2]; size_t offs[2];
; #pragma unroll
;         for (int u = 0; u < 2; ++u) {
;             const int m = (u ? idx2 : idx) >> 7; tt[u] = m & (SEQ - 1); offs[u] = (size_t)m * 1024 + c;
; #pragma unroll
;             for (int dt = 0; dt < 3; ++dt) { const size_t o2 = offs[u] - (size_t)((tt[u] - 2 + dt >= 0) ? (2 - dt) : 0) * 1024; cv[u][dt] = *(const v4u*)(CG + o2); hv[u][dt] = *(const v4u*)(HX + o2); }
;             bv[u] = *(const v4u*)(BG + offs[u]);
;         }
; #pragma unroll
;         for (int u = 0; u < 2; ++u) {
;             float y[8];
; #pragma unroll
;             for (int j = 0; j < 8; ++j) y[j] = bb[j];
; #pragma unroll
;             for (int dt = 0; dt < 3; ++dt) {
;                 const float on = (tt[u] - 2 + dt >= 0) ? 1.f : 0.f;
;                 const float* wp = dt == 0 ? w0 : (dt == 1 ? w1 : w2);
;                 const v4u cq = cv[u][dt], hq = hv[u][dt];
;                 y[0] += on * wp[0] * (bflo(cq.x) * bflo(hq.x)); y[1] += on * wp[1] * (bfhi(cq.x) * bfhi(hq.x));
;                 y[2] += on * wp[2] * (bflo(cq.y) * bflo(hq.y)); y[3] += on * wp[3] * (bfhi(cq.y) * bfhi(hq.y));
;                 y[4] += on * wp[4] * (bflo(cq.z) * bflo(hq.z)); y[5] += on * wp[5] * (bfhi(cq.z) * bfhi(hq.z));
;                 y[6] += on * wp[6] * (bflo(cq.w) * bflo(hq.w)); y[7] += on * wp[7] * (bfhi(cq.w) * bfhi(hq.w));
;             }
;             const v4u bq = bv[u];
;             v4u w; w.x = pk2(y[0] * bflo(bq.x), y[1] * bfhi(bq.x)); w.y = pk2(y[2] * bflo(bq.y), y[3] * bfhi(bq.y)); w.z = pk2(y[4] * bflo(bq.z), y[5] * bfhi(bq.z)); w.w = pk2(y[6] * bflo(bq.w), y[7] * bfhi(bq.w));
;             if (u == 0 || idx2 != idx) *(v4u*)(O3 + offs[u]) = w;
.LBB0_2217:
	v_add_u32_e32 v35, s70, v64
	s_mov_b32 s10, 0x400000
	v_cmp_gt_i32_e32 vcc, s10, v35
	v_mov_b32_e32 v65, 0xfffff800
	v_mov_b32_e32 v72, 0xfffffc00
	v_cndmask_b32_e32 v34, v64, v35, vcc
	v_ashrrev_i32_e32 v36, 7, v34
	v_and_b32_e32 v95, 0x1fff, v36
	v_ashrrev_i32_e32 v37, 31, v36
	v_lshlrev_b64 v[92:93], 10, v[36:37]
	v_cmp_gt_u32_e32 vcc, 2, v95
	v_or_b32_e32 v92, v92, v32
	v_cmp_ne_u32_e64 s[38:39], v64, v34
	v_cndmask_b32_e64 v37, -1, 0, vcc
	v_cndmask_b32_e64 v36, v65, 0, vcc
	v_lshl_add_u64 v[36:37], v[36:37], 0, v[92:93]
	v_ashrrev_i32_e32 v64, 7, v64
	v_lshlrev_b64 v[36:37], 1, v[36:37]
	v_and_b32_e32 v34, 0x1fff, v64
	v_lshl_add_u64 v[38:39], s[48:49], 0, v[36:37]
	v_lshl_add_u64 v[36:37], s[4:5], 0, v[36:37]
	v_cmp_eq_u32_e32 vcc, 0, v95
	v_cmp_gt_u32_e64 s[40:41], 2, v34
	global_load_dwordx4 v[60:63], v[38:39], off nt
	global_load_dwordx4 v[52:55], v[36:37], off nt
	v_cndmask_b32_e64 v37, -1, 0, vcc
	v_cndmask_b32_e64 v36, v72, 0, vcc
	v_cndmask_b32_e64 v66, v65, 0, s[40:41]
	v_ashrrev_i32_e32 v65, 31, v64
	v_lshl_add_u64 v[36:37], v[36:37], 0, v[92:93]
	v_cndmask_b32_e64 v67, -1, 0, s[40:41]
	v_lshlrev_b64 v[80:81], 10, v[64:65]
	v_cmp_lt_u32_e64 s[40:41], 1, v34
	v_lshlrev_b64 v[36:37], 1, v[36:37]
	v_or_b32_e32 v80, v80, v32
	v_cndmask_b32_e64 v94, 0, 1.0, s[40:41]
	v_cmp_eq_u32_e64 s[40:41], 0, v34
	v_lshl_add_u64 v[38:39], s[48:49], 0, v[36:37]
	v_lshl_add_u64 v[36:37], s[4:5], 0, v[36:37]
	v_lshl_add_u64 v[64:65], v[66:67], 0, v[80:81]
	v_cndmask_b32_e64 v73, -1, 0, s[40:41]
	v_cndmask_b32_e64 v72, v72, 0, s[40:41]
	global_load_dwordx4 v[56:59], v[38:39], off nt
	global_load_dwordx4 v[48:51], v[36:37], off nt
	v_lshlrev_b64 v[36:37], 1, v[92:93]
	v_lshlrev_b64 v[68:69], 1, v[64:65]
	v_lshl_add_u64 v[72:73], v[72:73], 0, v[80:81]
	v_lshl_add_u64 v[38:39], s[48:49], 0, v[36:37]
	v_lshl_add_u64 v[64:65], s[48:49], 0, v[68:69]
	v_lshl_add_u64 v[68:69], s[4:5], 0, v[68:69]
	v_lshlrev_b64 v[72:73], 1, v[72:73]
	v_lshlrev_b64 v[98:99], 1, v[80:81]
	global_load_dwordx4 v[44:47], v[38:39], off nt
	v_lshl_add_u64 v[74:75], s[48:49], 0, v[72:73]
	global_load_dwordx4 v[68:71], v[68:69], off nt
	v_lshl_add_u64 v[38:39], s[4:5], 0, v[36:37]
	v_lshl_add_u64 v[36:37], s[46:47], 0, v[36:37]
	v_lshl_add_u64 v[72:73], s[4:5], 0, v[72:73]
	v_lshl_add_u64 v[80:81], s[48:49], 0, v[98:99]
	global_load_dwordx4 v[40:43], v[38:39], off nt
	global_load_dwordx4 v[76:79], v[74:75], off nt
	v_lshl_add_u64 v[84:85], s[4:5], 0, v[98:99]
	global_load_dwordx4 v[64:67], v[64:65], off nt
	v_cndmask_b32_e64 v96, 1.0, 0, s[40:41]
	global_load_dwordx4 v[80:83], v[80:81], off nt
	s_waitcnt vmcnt(4)
	v_lshlrev_b32_e32 v102, 16, v68
	global_load_dwordx4 v[72:75], v[72:73], off nt
	v_and_b32_e32 v103, 0xffff0000, v68
	global_load_dwordx4 v[36:39], v[36:37], off nt
	v_lshlrev_b32_e32 v68, 16, v69
	global_load_dwordx4 v[88:91], v[84:85], off nt
	v_lshl_add_u64 v[84:85], s[46:47], 0, v[98:99]
	global_load_dwordx4 v[84:87], v[84:85], off nt
	s_waitcnt vmcnt(5)
	v_lshlrev_b32_e32 v100, 16, v64
	v_and_b32_e32 v101, 0xffff0000, v64
	v_pk_mul_f32 v[100:101], v[100:101], v[102:103]
	v_pk_mul_f32 v[102:103], v[24:25], v[94:95] op_sel_hi:[1,0]
	v_and_b32_e32 v69, 0xffff0000, v69
	v_pk_fma_f32 v[100:101], v[102:103], v[100:101], v[28:29]
	v_lshlrev_b32_e32 v102, 16, v76
	v_and_b32_e32 v103, 0xffff0000, v76
	v_lshlrev_b32_e32 v76, 16, v77
	v_and_b32_e32 v77, 0xffff0000, v77
	v_lshl_add_u64 v[98:99], s[50:51], 0, v[98:99]
	s_waitcnt vmcnt(3)
	v_lshlrev_b32_e32 v104, 16, v72
	v_and_b32_e32 v105, 0xffff0000, v72
	v_pk_mul_f32 v[102:103], v[102:103], v[104:105]
	v_pk_mul_f32 v[104:105], v[0:1], v[96:97] op_sel_hi:[1,0]
	v_lshlrev_b32_e32 v72, 16, v73
	v_pk_fma_f32 v[100:101], v[104:105], v[102:103], v[100:101]
	v_lshlrev_b32_e32 v102, 16, v80
	v_and_b32_e32 v103, 0xffff0000, v80
	s_waitcnt vmcnt(1)
	v_lshlrev_b32_e32 v104, 16, v88
	v_and_b32_e32 v105, 0xffff0000, v88
	v_pk_mul_f32 v[102:103], v[102:103], v[104:105]
	v_and_b32_e32 v73, 0xffff0000, v73
	v_pk_fma_f32 v[100:101], v[4:5], v[102:103], v[100:101]
	s_waitcnt vmcnt(0)
	v_lshlrev_b32_e32 v102, 16, v84
	v_and_b32_e32 v103, 0xffff0000, v84
	v_pk_mul_f32 v[100:101], v[100:101], v[102:103]
	v_pk_mul_f32 v[72:73], v[76:77], v[72:73]
	v_cvt_pk_bf16_f32 v64, v100, v101
	v_lshlrev_b32_e32 v100, 16, v65
	v_and_b32_e32 v101, 0xffff0000, v65
	v_pk_mul_f32 v[68:69], v[100:101], v[68:69]
	v_pk_mul_f32 v[100:101], v[26:27], v[94:95] op_sel_hi:[1,0]
	v_pk_mul_f32 v[76:77], v[2:3], v[96:97] op_sel_hi:[1,0]
	v_pk_fma_f32 v[68:69], v[100:101], v[68:69], v[30:31]
	s_nop 0
	v_pk_fma_f32 v[68:69], v[76:77], v[72:73], v[68:69]
	v_lshlrev_b32_e32 v72, 16, v81
	v_and_b32_e32 v73, 0xffff0000, v81
	v_lshlrev_b32_e32 v76, 16, v89
	v_and_b32_e32 v77, 0xffff0000, v89
	v_pk_mul_f32 v[72:73], v[72:73], v[76:77]
	v_lshlrev_b32_e32 v76, 16, v74
	v_pk_fma_f32 v[68:69], v[6:7], v[72:73], v[68:69]
	v_lshlrev_b32_e32 v72, 16, v85
	v_and_b32_e32 v73, 0xffff0000, v85
	v_pk_mul_f32 v[68:69], v[68:69], v[72:73]
	v_lshlrev_b32_e32 v72, 16, v70
	v_cvt_pk_bf16_f32 v65, v68, v69
	v_lshlrev_b32_e32 v68, 16, v66
	v_and_b32_e32 v69, 0xffff0000, v66
	v_and_b32_e32 v73, 0xffff0000, v70
	v_pk_mul_f32 v[68:69], v[68:69], v[72:73]
	v_pk_mul_f32 v[72:73], v[16:17], v[94:95] op_sel_hi:[1,0]
	v_and_b32_e32 v77, 0xffff0000, v74
	v_pk_fma_f32 v[68:69], v[72:73], v[68:69], v[20:21]
	v_lshlrev_b32_e32 v72, 16, v78
	v_and_b32_e32 v73, 0xffff0000, v78
	v_pk_mul_f32 v[72:73], v[72:73], v[76:77]
	v_pk_mul_f32 v[76:77], v[8:9], v[96:97] op_sel_hi:[1,0]
	v_lshlrev_b32_e32 v70, 16, v71
	v_pk_fma_f32 v[68:69], v[76:77], v[72:73], v[68:69]
	v_lshlrev_b32_e32 v72, 16, v82
	v_and_b32_e32 v73, 0xffff0000, v82
	v_lshlrev_b32_e32 v76, 16, v90
	v_and_b32_e32 v77, 0xffff0000, v90
	v_pk_mul_f32 v[72:73], v[72:73], v[76:77]
	v_and_b32_e32 v71, 0xffff0000, v71
	v_pk_fma_f32 v[68:69], v[12:13], v[72:73], v[68:69]
	v_lshlrev_b32_e32 v72, 16, v86
	v_and_b32_e32 v73, 0xffff0000, v86
	v_pk_mul_f32 v[68:69], v[68:69], v[72:73]
	v_lshlrev_b32_e32 v72, 16, v75
	v_cvt_pk_bf16_f32 v66, v68, v69
	v_lshlrev_b32_e32 v68, 16, v67
	v_and_b32_e32 v69, 0xffff0000, v67
	v_pk_mul_f32 v[68:69], v[68:69], v[70:71]
	v_pk_mul_f32 v[70:71], v[18:19], v[94:95] op_sel_hi:[1,0]
	v_and_b32_e32 v73, 0xffff0000, v75
	v_pk_fma_f32 v[68:69], v[70:71], v[68:69], v[22:23]
	v_lshlrev_b32_e32 v70, 16, v79
	v_and_b32_e32 v71, 0xffff0000, v79
	v_pk_mul_f32 v[70:71], v[70:71], v[72:73]
	v_pk_mul_f32 v[72:73], v[10:11], v[96:97] op_sel_hi:[1,0]
	s_nop 0
	v_pk_fma_f32 v[68:69], v[72:73], v[70:71], v[68:69]
	v_lshlrev_b32_e32 v70, 16, v83
	v_and_b32_e32 v71, 0xffff0000, v83
	v_lshlrev_b32_e32 v72, 16, v91
	v_and_b32_e32 v73, 0xffff0000, v91
	v_pk_mul_f32 v[70:71], v[70:71], v[72:73]
	s_nop 0
	v_pk_fma_f32 v[68:69], v[14:15], v[70:71], v[68:69]
	v_lshlrev_b32_e32 v70, 16, v87
	v_and_b32_e32 v71, 0xffff0000, v87
	v_pk_mul_f32 v[68:69], v[68:69], v[70:71]
	s_nop 0
	v_cvt_pk_bf16_f32 v67, v68, v69
	global_store_dwordx4 v[98:99], v[64:67], off nt
	s_and_saveexec_b64 s[10:11], s[38:39]
	s_cbranch_execz .LBB0_2216
; __device__ __forceinline__ unsigned pk2(float lo, float hi) { const f32x2_t v = {lo, hi}; const bf16x2_t b = __builtin_convertvector(v, bf16x2_t); return __builtin_bit_cast(unsigned, b); }
; __device__ __forceinline__ void sc_conv(const bf16* BG, const bf16* CG, const bf16* HX, const float* cw, const float* cb, bf16* O3, int gt, int ngt) {
;     ...
; #pragma unroll
;         for (int u = 0; u < 2; ++u) {
;             float y[8];
; #pragma unroll
;             for (int j = 0; j < 8; ++j) y[j] = bb[j];
; #pragma unroll
;             for (int dt = 0; dt < 3; ++dt) {
;                 const float on = (tt[u] - 2 + dt >= 0) ? 1.f : 0.f;
;                 const float* wp = dt == 0 ? w0 : (dt == 1 ? w1 : w2);
;                 const v4u cq = cv[u][dt], hq = hv[u][dt];
;                 y[0] += on * wp[0] * (bflo(cq.x) * bflo(hq.x)); y[1] += on * wp[1] * (bfhi(cq.x) * bfhi(hq.x));
;                 y[2] += on * wp[2] * (bflo(cq.y) * bflo(hq.y)); y[3] += on * wp[3] * (bfhi(cq.y) * bfhi(hq.y));
;                 y[4] += on * wp[4] * (bflo(cq.z) * bflo(hq.z)); y[5] += on * wp[5] * (bfhi(cq.z) * bfhi(hq.z));
;                 y[6] += on * wp[6] * (bflo(cq.w) * bflo(hq.w)); y[7] += on * wp[7] * (bfhi(cq.w) * bfhi(hq.w));
;             }
;             const v4u bq = bv[u];
;             v4u w; w.x = pk2(y[0] * bflo(bq.x), y[1] * bfhi(bq.x)); w.y = pk2(y[2] * bflo(bq.y), y[3] * bfhi(bq.y)); w.z = pk2(y[4] * bflo(bq.z), y[5] * bfhi(bq.z)); w.w = pk2(y[6] * bflo(bq.w), y[7] * bfhi(bq.w));
;             if (u == 0 || idx2 != idx) *(v4u*)(O3 + offs[u]) = w;
	v_cmp_lt_u32_e64 s[38:39], 1, v95
	v_lshlrev_b32_e32 v68, 16, v60
	v_and_b32_e32 v69, 0xffff0000, v60
	v_cndmask_b32_e64 v34, 0, 1.0, s[38:39]
	v_lshlrev_b32_e32 v70, 16, v52
	v_and_b32_e32 v71, 0xffff0000, v52
	v_pk_mul_f32 v[68:69], v[68:69], v[70:71]
	v_pk_mul_f32 v[70:71], v[24:25], v[34:35] op_sel_hi:[1,0]
	v_cndmask_b32_e64 v64, 1.0, 0, vcc
	v_pk_fma_f32 v[68:69], v[68:69], v[70:71], v[28:29]
	v_lshlrev_b32_e32 v70, 16, v56
	v_and_b32_e32 v71, 0xffff0000, v56
	v_lshlrev_b32_e32 v72, 16, v48
	v_and_b32_e32 v73, 0xffff0000, v48
	v_lshlrev_b32_e32 v60, 16, v61
	v_and_b32_e32 v61, 0xffff0000, v61
	v_lshlrev_b32_e32 v52, 16, v53
	v_and_b32_e32 v53, 0xffff0000, v53
	v_pk_mul_f32 v[70:71], v[70:71], v[72:73]
	v_pk_mul_f32 v[72:73], v[0:1], v[64:65] op_sel_hi:[1,0]
	v_pk_mul_f32 v[52:53], v[60:61], v[52:53]
	v_pk_mul_f32 v[60:61], v[26:27], v[34:35] op_sel_hi:[1,0]
	v_lshlrev_b32_e32 v56, 16, v57
	v_and_b32_e32 v57, 0xffff0000, v57
	v_lshlrev_b32_e32 v48, 16, v49
	v_and_b32_e32 v49, 0xffff0000, v49
	v_pk_fma_f32 v[68:69], v[70:71], v[72:73], v[68:69]
	v_lshlrev_b32_e32 v70, 16, v44
	v_and_b32_e32 v71, 0xffff0000, v44
	v_lshlrev_b32_e32 v72, 16, v40
	v_and_b32_e32 v73, 0xffff0000, v40
	v_pk_fma_f32 v[52:53], v[52:53], v[60:61], v[30:31]
	v_pk_mul_f32 v[48:49], v[56:57], v[48:49]
	v_pk_mul_f32 v[56:57], v[2:3], v[64:65] op_sel_hi:[1,0]
	v_lshlrev_b32_e32 v44, 16, v45
	v_and_b32_e32 v45, 0xffff0000, v45
	v_lshlrev_b32_e32 v40, 16, v41
	v_and_b32_e32 v41, 0xffff0000, v41
	v_pk_fma_f32 v[48:49], v[48:49], v[56:57], v[52:53]
	v_pk_mul_f32 v[40:41], v[44:45], v[40:41]
	v_lshlrev_b32_e32 v44, 16, v37
	v_pk_fma_f32 v[40:41], v[6:7], v[40:41], v[48:49]
	v_and_b32_e32 v45, 0xffff0000, v37
	v_pk_mul_f32 v[40:41], v[40:41], v[44:45]
	v_lshlrev_b32_e32 v44, 16, v54
	v_cvt_pk_bf16_f32 v37, v40, v41
	v_lshlrev_b32_e32 v40, 16, v62
	v_and_b32_e32 v41, 0xffff0000, v62
	v_and_b32_e32 v45, 0xffff0000, v54
	v_pk_mul_f32 v[40:41], v[40:41], v[44:45]
	v_pk_mul_f32 v[44:45], v[16:17], v[34:35] op_sel_hi:[1,0]
	v_lshlrev_b32_e32 v48, 16, v50
	v_pk_fma_f32 v[40:41], v[40:41], v[44:45], v[20:21]
	v_lshlrev_b32_e32 v44, 16, v58
	v_and_b32_e32 v45, 0xffff0000, v58
	v_and_b32_e32 v49, 0xffff0000, v50
	v_pk_mul_f32 v[44:45], v[44:45], v[48:49]
	v_pk_mul_f32 v[48:49], v[8:9], v[64:65] op_sel_hi:[1,0]
	v_pk_mul_f32 v[70:71], v[70:71], v[72:73]
	v_pk_fma_f32 v[40:41], v[44:45], v[48:49], v[40:41]
	v_lshlrev_b32_e32 v44, 16, v46
	v_and_b32_e32 v45, 0xffff0000, v46
	v_lshlrev_b32_e32 v48, 16, v42
	v_and_b32_e32 v49, 0xffff0000, v42
	v_pk_mul_f32 v[44:45], v[44:45], v[48:49]
	v_lshlrev_b32_e32 v48, 16, v51
	v_pk_fma_f32 v[40:41], v[12:13], v[44:45], v[40:41]
	v_lshlrev_b32_e32 v44, 16, v38
	v_and_b32_e32 v45, 0xffff0000, v38
	v_pk_mul_f32 v[40:41], v[40:41], v[44:45]
	v_lshlrev_b32_e32 v44, 16, v55
	v_cvt_pk_bf16_f32 v38, v40, v41
	v_lshlrev_b32_e32 v40, 16, v63
	v_and_b32_e32 v41, 0xffff0000, v63
	v_and_b32_e32 v45, 0xffff0000, v55
	v_pk_mul_f32 v[40:41], v[40:41], v[44:45]
	v_pk_mul_f32 v[44:45], v[18:19], v[34:35] op_sel_hi:[1,0]
	v_and_b32_e32 v49, 0xffff0000, v51
	v_pk_fma_f32 v[40:41], v[40:41], v[44:45], v[22:23]
	v_lshlrev_b32_e32 v44, 16, v59
	v_and_b32_e32 v45, 0xffff0000, v59
	v_pk_mul_f32 v[44:45], v[44:45], v[48:49]
	v_pk_mul_f32 v[48:49], v[10:11], v[64:65] op_sel_hi:[1,0]
	v_lshlrev_b32_e32 v42, 16, v43
	v_pk_fma_f32 v[40:41], v[44:45], v[48:49], v[40:41]
	v_lshlrev_b32_e32 v44, 16, v47
	v_and_b32_e32 v45, 0xffff0000, v47
	v_and_b32_e32 v43, 0xffff0000, v43
	v_pk_mul_f32 v[42:43], v[44:45], v[42:43]
	v_pk_fma_f32 v[68:69], v[4:5], v[70:71], v[68:69]
	v_lshlrev_b32_e32 v70, 16, v36
	v_and_b32_e32 v71, 0xffff0000, v36
	v_pk_fma_f32 v[40:41], v[14:15], v[42:43], v[40:41]
	v_lshlrev_b32_e32 v42, 16, v39
	v_and_b32_e32 v43, 0xffff0000, v39
	v_pk_mul_f32 v[68:69], v[68:69], v[70:71]
	v_pk_mul_f32 v[40:41], v[40:41], v[42:43]
	v_lshl_add_u64 v[66:67], v[92:93], 1, s[50:51]
	v_cvt_pk_bf16_f32 v36, v68, v69
	v_cvt_pk_bf16_f32 v39, v40, v41
	global_store_dwordx4 v[66:67], v[36:39], off nt
	s_branch .LBB0_2216

; __device__ __forceinline__ f32x4 bf4(v2u u) { return (f32x4){bflo(u.x), bfhi(u.x), bflo(u.y), bfhi(u.y)}; }
; template <int CTRL> __device__ __forceinline__ float dpp_f(float x) { return __builtin_bit_cast(float, __builtin_amdgcn_update_dpp(0, __builtin_bit_cast(int, x), CTRL, 0xf, 0xf, true)); }
; __global__ void __launch_bounds__(NTHR, 2) fwd_megakernel(Args a) {
;     ...
;     for (int m0 = gw; m0 < M; m0 += 4 * ngw) {
;         f32x4 v[4][4]; f32x4 pr[4];
; #pragma unroll
;         for (int u = 0; u < 4; ++u) { const int m = m0 + u * ngw < M ? m0 + u * ngw : m0;
;             pr[u] = *(const f32x4*)(RS + (size_t)m * 16 + 4 * (lane & 3));
; #pragma unroll
;             for (int j = 0; j < 4; ++j) v[u][j] = bf4(*(const v2u*)(HB + (size_t)m * 1024 + 4 * lane + 256 * j)); }
; #pragma unroll
;         for (int u = 0; u < 4; ++u) { const int m = m0 + u * ngw; if (m >= M) break; f32x4* xr = (f32x4*)(out + (size_t)m * 1024) + lane;
;             float s = (pr[u][0] + pr[u][1]) + (pr[u][2] + pr[u][3]); s += dpp_f<0xB1>(s); s += dpp_f<0x4E>(s);
;             const float r = 1.0f / sqrtf(s * (1.0f / 1024.0f) + 1e-6f);
;             xr[0] = v[u][0] * r * g0; xr[64] = v[u][1] * r * g1; xr[128] = v[u][2] * r * g2; xr[192] = v[u][3] * r * g3; }
.LBB0_2532:
	s_add_i32 s12, s33, s2
	s_cmp_lt_i32 s12, 0x8000
	s_cselect_b32 s0, s12, s2
	s_ashr_i32 s1, s0, 31
	s_lshl_b64 s[16:17], s[0:1], 6
	s_lshl_b64 s[0:1], s[0:1], 11
	s_add_i32 s8, s94, s2
	s_cmp_lt_i32 s8, 0x8000
	s_cselect_b64 s[10:11], -1, 0
	s_and_b64 s[4:5], s[10:11], exec
	s_cselect_b32 s4, s8, s2
	s_ashr_i32 s5, s4, 31
	v_readlane_b32 s3, v254, 8
	s_lshl_b64 s[18:19], s[4:5], 6
	s_lshl_b64 s[20:21], s[4:5], 11
	s_add_i32 s4, s3, s2
	s_cmp_lt_i32 s4, 0x8000
	s_cselect_b64 s[6:7], -1, 0
	s_and_b64 s[22:23], s[6:7], exec
	s_cselect_b32 s22, s4, s2
	s_ashr_i32 s3, s2, 31
	s_lshl_b64 s[24:25], s[2:3], 11
	s_waitcnt vmcnt(5)
	v_lshl_add_u64 v[16:17], v[30:31], 0, s[24:25]
	s_lshl_b64 s[24:25], s[2:3], 6
	v_lshl_add_u64 v[18:19], v[28:29], 0, s[24:25]
	global_load_dwordx2 v[64:65], v[16:17], off offset:1536 nt
	global_load_dwordx2 v[66:67], v[16:17], off offset:1024 nt
	global_load_dwordx2 v[68:69], v[16:17], off offset:512 nt
	global_load_dwordx4 v[60:63], v[18:19], off nt
	global_load_dwordx2 v[70:71], v[16:17], off nt
	s_ashr_i32 s23, s22, 31
	s_lshl_b64 s[24:25], s[22:23], 11
	v_lshl_add_u64 v[72:73], v[30:31], 0, s[24:25]
	v_lshl_add_u64 v[16:17], v[28:29], 0, s[16:17]
	global_load_dwordx2 v[38:39], v[72:73], off offset:512 nt
	global_load_dwordx2 v[36:37], v[72:73], off offset:1024 nt
	global_load_dwordx2 v[34:35], v[72:73], off offset:1536 nt
	v_lshl_add_u64 v[18:19], v[30:31], 0, s[0:1]
	global_load_dwordx4 v[24:27], v[16:17], off nt
	global_load_dwordx2 v[50:51], v[18:19], off nt
	global_load_dwordx2 v[52:53], v[18:19], off offset:512 nt
	global_load_dwordx2 v[54:55], v[18:19], off offset:1024 nt
	global_load_dwordx2 v[56:57], v[18:19], off offset:1536 nt
	v_lshl_add_u64 v[16:17], v[28:29], 0, s[18:19]
	v_lshl_add_u64 v[18:19], v[30:31], 0, s[20:21]
	global_load_dwordx4 v[20:23], v[16:17], off nt
	global_load_dwordx2 v[48:49], v[18:19], off nt
	global_load_dwordx2 v[46:47], v[18:19], off offset:512 nt
	global_load_dwordx2 v[44:45], v[18:19], off offset:1024 nt
	global_load_dwordx2 v[42:43], v[18:19], off offset:1536 nt
	s_lshl_b64 s[0:1], s[22:23], 6
	v_lshl_add_u64 v[74:75], v[28:29], 0, s[0:1]
	global_load_dwordx4 v[16:19], v[74:75], off nt
	global_load_dwordx2 v[40:41], v[72:73], off nt
	s_lshl_b64 s[0:1], s[2:3], 12
	v_lshl_add_u64 v[76:77], v[32:33], 0, s[0:1]
	s_cmpk_gt_i32 s12, 0x7fff
	s_waitcnt vmcnt(19)
	v_lshlrev_b32_e32 v72, 16, v64
	v_and_b32_e32 v73, 0xffff0000, v64
	s_waitcnt vmcnt(16)
	v_mov_b32_e32 v80, v61
	v_mov_b32_e32 v81, v62
	v_mov_b32_e32 v61, v63
	v_pk_add_f32 v[60:61], v[80:81], v[60:61]
	s_waitcnt vmcnt(15)
	v_lshlrev_b32_e32 v62, 16, v71
	v_add_f32_e32 v60, v60, v61
	v_lshlrev_b32_e32 v64, 16, v65
	v_and_b32_e32 v65, 0xffff0000, v65
	v_add_f32_dpp v60, v60, v60 quad_perm:[1,0,3,2] row_mask:0xf bank_mask:0xf bound_ctrl:1
	v_lshlrev_b32_e32 v74, 16, v66
	v_and_b32_e32 v75, 0xffff0000, v66
	v_add_f32_dpp v60, v60, v60 quad_perm:[2,3,0,1] row_mask:0xf bank_mask:0xf bound_ctrl:1
	v_fmamk_f32 v60, v60, 0x3a800000, v58
	v_mul_f32_e32 v61, 0x4f800000, v60
	v_cmp_gt_f32_e32 vcc, s14, v60
	v_lshlrev_b32_e32 v66, 16, v67
	v_and_b32_e32 v67, 0xffff0000, v67
	v_cndmask_b32_e32 v63, v60, v61, vcc
	v_sqrt_f32_e32 v80, v63
	v_lshlrev_b32_e32 v60, 16, v70
	v_and_b32_e32 v61, 0xffff0000, v70
	v_lshlrev_b32_e32 v78, 16, v68
	v_add_u32_e32 v70, -1, v80
	v_add_u32_e32 v81, 1, v80
	v_fma_f32 v82, -v70, v80, v63
	v_fma_f32 v83, -v81, v80, v63
	v_cmp_ge_f32_e64 s[0:1], 0, v82
	v_and_b32_e32 v79, 0xffff0000, v68
	v_lshlrev_b32_e32 v68, 16, v69
	v_cndmask_b32_e64 v70, v80, v70, s[0:1]
	v_cmp_lt_f32_e64 s[0:1], 0, v83
	v_and_b32_e32 v69, 0xffff0000, v69
	s_nop 0
	v_cndmask_b32_e64 v70, v70, v81, s[0:1]
	v_mul_f32_e32 v80, 0x37800000, v70
	v_cndmask_b32_e32 v70, v70, v80, vcc
	v_cmp_class_f32_e32 vcc, v63, v59
	s_nop 1
	v_cndmask_b32_e32 v70, v70, v63, vcc
	v_div_scale_f32 v80, s[0:1], v70, v70, 1.0
	v_rcp_f32_e32 v81, v80
	v_and_b32_e32 v63, 0xffff0000, v71
	v_div_scale_f32 v71, vcc, 1.0, v70, 1.0
	v_fma_f32 v82, -v80, v81, 1.0
	v_fmac_f32_e32 v81, v82, v81
	v_mul_f32_e32 v82, v71, v81
	v_fma_f32 v83, -v80, v82, v71
	v_fmac_f32_e32 v82, v83, v81
	v_fma_f32 v71, -v80, v82, v71
	v_div_fmas_f32 v71, v71, v81, v82
	v_div_fixup_f32 v70, v71, v70, 1.0
	v_pk_mul_f32 v[60:61], v[70:71], v[60:61] op_sel_hi:[0,1]
	v_pk_mul_f32 v[62:63], v[70:71], v[62:63] op_sel_hi:[0,1]
	v_pk_mul_f32 v[78:79], v[70:71], v[78:79] op_sel_hi:[0,1]
	v_pk_mul_f32 v[68:69], v[70:71], v[68:69] op_sel_hi:[0,1]
	v_pk_mul_f32 v[74:75], v[70:71], v[74:75] op_sel_hi:[0,1]
	v_pk_mul_f32 v[80:81], v[70:71], v[66:67] op_sel_hi:[0,1]
	v_pk_mul_f32 v[72:73], v[70:71], v[72:73] op_sel_hi:[0,1]
	v_pk_mul_f32 v[82:83], v[70:71], v[64:65] op_sel_hi:[0,1]
	v_pk_mul_f32 v[62:63], v[2:3], v[62:63]
	v_pk_mul_f32 v[60:61], v[0:1], v[60:61]
	v_pk_mul_f32 v[66:67], v[6:7], v[68:69]
	v_pk_mul_f32 v[64:65], v[4:5], v[78:79]
	v_pk_mul_f32 v[70:71], v[10:11], v[80:81]
	v_pk_mul_f32 v[68:69], v[8:9], v[74:75]
	v_pk_mul_f32 v[74:75], v[14:15], v[82:83]
	v_pk_mul_f32 v[72:73], v[12:13], v[72:73]
	global_store_dwordx4 v[76:77], v[60:63], off nt
	global_store_dwordx4 v[76:77], v[64:67], off offset:1024 nt
	global_store_dwordx4 v[76:77], v[68:71], off offset:2048 nt
	global_store_dwordx4 v[76:77], v[72:75], off offset:3072 nt
	s_cbranch_scc1 .LBB0_2531
; template <int CTRL> __device__ __forceinline__ float dpp_f(float x) { return __builtin_bit_cast(float, __builtin_amdgcn_update_dpp(0, __builtin_bit_cast(int, x), CTRL, 0xf, 0xf, true)); }
; __global__ void __launch_bounds__(NTHR, 2) fwd_megakernel(Args a) {
;     ...
; #pragma unroll
;         for (int u = 0; u < 4; ++u) { const int m = m0 + u * ngw; if (m >= M) break; f32x4* xr = (f32x4*)(out + (size_t)m * 1024) + lane;
;             float s = (pr[u][0] + pr[u][1]) + (pr[u][2] + pr[u][3]); s += dpp_f<0xB1>(s); s += dpp_f<0x4E>(s);
;             const float r = 1.0f / sqrtf(s * (1.0f / 1024.0f) + 1e-6f);
;             xr[0] = v[u][0] * r * g0; xr[64] = v[u][1] * r * g1; xr[128] = v[u][2] * r * g2; xr[192] = v[u][3] * r * g3; }
	s_waitcnt vmcnt(15)
	v_mov_b32_e32 v68, v25
	v_mov_b32_e32 v69, v26
	v_mov_b32_e32 v25, v27
	v_pk_add_f32 v[24:25], v[68:69], v[24:25]
	s_waitcnt vmcnt(14)
	v_lshlrev_b32_e32 v66, 16, v50
	v_add_f32_e32 v24, v24, v25
	v_and_b32_e32 v67, 0xffff0000, v50
	s_ashr_i32 s13, s12, 31
	v_add_f32_dpp v24, v24, v24 quad_perm:[1,0,3,2] row_mask:0xf bank_mask:0xf bound_ctrl:1
	s_waitcnt vmcnt(13)
	v_lshlrev_b32_e32 v64, 16, v52
	v_and_b32_e32 v65, 0xffff0000, v52
	v_add_f32_dpp v24, v24, v24 quad_perm:[2,3,0,1] row_mask:0xf bank_mask:0xf bound_ctrl:1
	v_fmamk_f32 v24, v24, 0x3a800000, v58
	v_mul_f32_e32 v25, 0x4f800000, v24
	v_cmp_gt_f32_e32 vcc, s14, v24
	v_lshlrev_b32_e32 v52, 16, v53
	v_and_b32_e32 v53, 0xffff0000, v53
	v_cndmask_b32_e32 v26, v24, v25, vcc
	v_sqrt_f32_e32 v27, v26
	v_lshlrev_b32_e32 v24, 16, v51
	v_and_b32_e32 v25, 0xffff0000, v51
	s_waitcnt vmcnt(12)
	v_lshlrev_b32_e32 v62, 16, v54
	v_add_u32_e32 v50, -1, v27
	v_fma_f32 v51, -v50, v27, v26
	v_cmp_ge_f32_e64 s[0:1], 0, v51
	v_add_u32_e32 v51, 1, v27
	v_and_b32_e32 v63, 0xffff0000, v54
	v_cndmask_b32_e64 v50, v27, v50, s[0:1]
	v_fma_f32 v27, -v51, v27, v26
	v_cmp_lt_f32_e64 s[0:1], 0, v27
	v_lshlrev_b32_e32 v54, 16, v55
	v_and_b32_e32 v55, 0xffff0000, v55
	v_cndmask_b32_e64 v27, v50, v51, s[0:1]
	v_mul_f32_e32 v50, 0x37800000, v27
	v_cndmask_b32_e32 v27, v27, v50, vcc
	v_cmp_class_f32_e32 vcc, v26, v59
	s_waitcnt vmcnt(11)
	v_lshlrev_b32_e32 v60, 16, v56
	v_and_b32_e32 v61, 0xffff0000, v56
	v_cndmask_b32_e32 v26, v27, v26, vcc
	v_div_scale_f32 v27, s[0:1], v26, v26, 1.0
	v_rcp_f32_e32 v68, v27
	s_lshl_b64 s[0:1], s[12:13], 12
	v_lshl_add_u64 v[50:51], v[32:33], 0, s[0:1]
	v_lshlrev_b32_e32 v56, 16, v57
	v_fma_f32 v69, -v27, v68, 1.0
	v_fmac_f32_e32 v68, v69, v68
	v_div_scale_f32 v69, vcc, 1.0, v26, 1.0
	v_mul_f32_e32 v70, v69, v68
	v_fma_f32 v71, -v27, v70, v69
	v_fmac_f32_e32 v70, v71, v68
	v_fma_f32 v27, -v27, v70, v69
	v_div_fmas_f32 v27, v27, v68, v70
	v_div_fixup_f32 v68, v27, v26, 1.0
	v_pk_mul_f32 v[66:67], v[68:69], v[66:67] op_sel_hi:[0,1]
	v_pk_mul_f32 v[24:25], v[68:69], v[24:25] op_sel_hi:[0,1]
	v_pk_mul_f32 v[26:27], v[2:3], v[24:25]
	v_pk_mul_f32 v[24:25], v[0:1], v[66:67]
	global_store_dwordx4 v[50:51], v[24:27], off nt
	v_and_b32_e32 v57, 0xffff0000, v57
	s_andn2_b64 vcc, exec, s[10:11]
	v_pk_mul_f32 v[24:25], v[68:69], v[64:65] op_sel_hi:[0,1]
	v_pk_mul_f32 v[26:27], v[68:69], v[52:53] op_sel_hi:[0,1]
	v_pk_mul_f32 v[26:27], v[6:7], v[26:27]
	v_pk_mul_f32 v[24:25], v[4:5], v[24:25]
	global_store_dwordx4 v[50:51], v[24:27], off offset:1024 nt
	s_nop 1
	v_pk_mul_f32 v[24:25], v[68:69], v[62:63] op_sel_hi:[0,1]
	v_pk_mul_f32 v[26:27], v[68:69], v[54:55] op_sel_hi:[0,1]
	v_pk_mul_f32 v[26:27], v[10:11], v[26:27]
	v_pk_mul_f32 v[24:25], v[8:9], v[24:25]
	global_store_dwordx4 v[50:51], v[24:27], off offset:2048 nt
	s_nop 1
	v_pk_mul_f32 v[24:25], v[68:69], v[60:61] op_sel_hi:[0,1]
	v_pk_mul_f32 v[26:27], v[68:69], v[56:57] op_sel_hi:[0,1]
	v_pk_mul_f32 v[26:27], v[14:15], v[26:27]
	v_pk_mul_f32 v[24:25], v[12:13], v[24:25]
	global_store_dwordx4 v[50:51], v[24:27], off offset:3072 nt
	s_cbranch_vccnz .LBB0_2531
; __device__ __forceinline__ f32x4 bf4(v2u u) { return (f32x4){bflo(u.x), bfhi(u.x), bflo(u.y), bfhi(u.y)}; }
; template <int CTRL> __device__ __forceinline__ float dpp_f(float x) { return __builtin_bit_cast(float, __builtin_amdgcn_update_dpp(0, __builtin_bit_cast(int, x), CTRL, 0xf, 0xf, true)); }
; __global__ void __launch_bounds__(NTHR, 2) fwd_megakernel(Args a) {
;     ...
;     for (int m0 = gw; m0 < M; m0 += 4 * ngw) {
;         f32x4 v[4][4]; f32x4 pr[4];
; #pragma unroll
;         for (int u = 0; u < 4; ++u) { const int m = m0 + u * ngw < M ? m0 + u * ngw : m0;
;             pr[u] = *(const f32x4*)(RS + (size_t)m * 16 + 4 * (lane & 3));
; #pragma unroll
;             for (int j = 0; j < 4; ++j) v[u][j] = bf4(*(const v2u*)(HB + (size_t)m * 1024 + 4 * lane + 256 * j)); }
; #pragma unroll
;         for (int u = 0; u < 4; ++u) { const int m = m0 + u * ngw; if (m >= M) break; f32x4* xr = (f32x4*)(out + (size_t)m * 1024) + lane;
;             float s = (pr[u][0] + pr[u][1]) + (pr[u][2] + pr[u][3]); s += dpp_f<0xB1>(s); s += dpp_f<0x4E>(s);
;             const float r = 1.0f / sqrtf(s * (1.0f / 1024.0f) + 1e-6f);
;             xr[0] = v[u][0] * r * g0; xr[64] = v[u][1] * r * g1; xr[128] = v[u][2] * r * g2; xr[192] = v[u][3] * r * g3; }
	s_waitcnt vmcnt(14)
	v_mov_b32_e32 v54, v21
	v_mov_b32_e32 v55, v22
	v_mov_b32_e32 v21, v23
	v_pk_add_f32 v[20:21], v[54:55], v[20:21]
	s_waitcnt vmcnt(13)
	v_lshlrev_b32_e32 v24, 16, v48
	v_add_f32_e32 v20, v20, v21
	v_and_b32_e32 v25, 0xffff0000, v48
	v_lshlrev_b32_e32 v26, 16, v49
	v_add_f32_dpp v20, v20, v20 quad_perm:[1,0,3,2] row_mask:0xf bank_mask:0xf bound_ctrl:1
	v_and_b32_e32 v27, 0xffff0000, v49
	s_ashr_i32 s9, s8, 31
	v_add_f32_dpp v20, v20, v20 quad_perm:[2,3,0,1] row_mask:0xf bank_mask:0xf bound_ctrl:1
	v_fmamk_f32 v20, v20, 0x3a800000, v58
	v_mul_f32_e32 v21, 0x4f800000, v20
	v_cmp_gt_f32_e32 vcc, s14, v20
	s_waitcnt vmcnt(12)
	v_lshlrev_b32_e32 v48, 16, v46
	v_and_b32_e32 v49, 0xffff0000, v46
	v_cndmask_b32_e32 v20, v20, v21, vcc
	v_sqrt_f32_e32 v21, v20
	v_lshlrev_b32_e32 v46, 16, v47
	v_and_b32_e32 v47, 0xffff0000, v47
	s_waitcnt vmcnt(11)
	v_lshlrev_b32_e32 v50, 16, v44
	v_add_u32_e32 v22, -1, v21
	v_fma_f32 v23, -v22, v21, v20
	v_cmp_ge_f32_e64 s[0:1], 0, v23
	v_add_u32_e32 v23, 1, v21
	v_and_b32_e32 v51, 0xffff0000, v44
	v_cndmask_b32_e64 v22, v21, v22, s[0:1]
	v_fma_f32 v21, -v23, v21, v20
	v_cmp_lt_f32_e64 s[0:1], 0, v21
	v_lshlrev_b32_e32 v44, 16, v45
	v_and_b32_e32 v45, 0xffff0000, v45
	v_cndmask_b32_e64 v21, v22, v23, s[0:1]
	v_mul_f32_e32 v22, 0x37800000, v21
	v_cndmask_b32_e32 v21, v21, v22, vcc
	v_cmp_class_f32_e32 vcc, v20, v59
	s_waitcnt vmcnt(10)
	v_lshlrev_b32_e32 v52, 16, v42
	v_and_b32_e32 v53, 0xffff0000, v42
	v_cndmask_b32_e32 v20, v21, v20, vcc
	v_div_scale_f32 v21, s[0:1], v20, v20, 1.0
	v_rcp_f32_e32 v22, v21
	s_lshl_b64 s[0:1], s[8:9], 12
	v_lshl_add_u64 v[54:55], v[32:33], 0, s[0:1]
	v_lshlrev_b32_e32 v42, 16, v43
	v_fma_f32 v23, -v21, v22, 1.0
	v_fmac_f32_e32 v22, v23, v22
	v_div_scale_f32 v23, vcc, 1.0, v20, 1.0
	v_mul_f32_e32 v56, v23, v22
	v_fma_f32 v57, -v21, v56, v23
	v_fmac_f32_e32 v56, v57, v22
	v_fma_f32 v21, -v21, v56, v23
	v_div_fmas_f32 v21, v21, v22, v56
	v_div_fixup_f32 v56, v21, v20, 1.0
	v_pk_mul_f32 v[20:21], v[56:57], v[24:25] op_sel_hi:[0,1]
	v_pk_mul_f32 v[22:23], v[56:57], v[26:27] op_sel_hi:[0,1]
	v_pk_mul_f32 v[22:23], v[2:3], v[22:23]
	v_pk_mul_f32 v[20:21], v[0:1], v[20:21]
	global_store_dwordx4 v[54:55], v[20:23], off nt
	v_and_b32_e32 v43, 0xffff0000, v43
	s_andn2_b64 vcc, exec, s[6:7]
	v_pk_mul_f32 v[20:21], v[56:57], v[48:49] op_sel_hi:[0,1]
	v_pk_mul_f32 v[22:23], v[56:57], v[46:47] op_sel_hi:[0,1]
	v_pk_mul_f32 v[22:23], v[6:7], v[22:23]
	v_pk_mul_f32 v[20:21], v[4:5], v[20:21]
	global_store_dwordx4 v[54:55], v[20:23], off offset:1024 nt
	s_nop 1
	v_pk_mul_f32 v[20:21], v[56:57], v[50:51] op_sel_hi:[0,1]
	v_pk_mul_f32 v[22:23], v[56:57], v[44:45] op_sel_hi:[0,1]
	v_pk_mul_f32 v[22:23], v[10:11], v[22:23]
	v_pk_mul_f32 v[20:21], v[8:9], v[20:21]
	global_store_dwordx4 v[54:55], v[20:23], off offset:2048 nt
	s_nop 1
	v_pk_mul_f32 v[20:21], v[56:57], v[52:53] op_sel_hi:[0,1]
	v_pk_mul_f32 v[22:23], v[56:57], v[42:43] op_sel_hi:[0,1]
	v_pk_mul_f32 v[22:23], v[14:15], v[22:23]
	v_pk_mul_f32 v[20:21], v[12:13], v[20:21]
	global_store_dwordx4 v[54:55], v[20:23], off offset:3072 nt
	s_cbranch_vccnz .LBB0_2531
	s_waitcnt vmcnt(13)
	v_mov_b32_e32 v42, v17
	v_mov_b32_e32 v43, v18
	v_mov_b32_e32 v17, v19
	v_pk_add_f32 v[16:17], v[42:43], v[16:17]
	s_waitcnt vmcnt(12)
	v_lshlrev_b32_e32 v20, 16, v40
	v_add_f32_e32 v16, v16, v17
	v_and_b32_e32 v21, 0xffff0000, v40
	v_lshlrev_b32_e32 v22, 16, v41
	v_add_f32_dpp v16, v16, v16 quad_perm:[1,0,3,2] row_mask:0xf bank_mask:0xf bound_ctrl:1
	v_and_b32_e32 v23, 0xffff0000, v41
	s_ashr_i32 s5, s4, 31
	v_add_f32_dpp v16, v16, v16 quad_perm:[2,3,0,1] row_mask:0xf bank_mask:0xf bound_ctrl:1
	v_fmamk_f32 v16, v16, 0x3a800000, v58
	v_mul_f32_e32 v17, 0x4f800000, v16
	v_cmp_gt_f32_e32 vcc, s14, v16
	v_lshlrev_b32_e32 v24, 16, v38
	v_and_b32_e32 v25, 0xffff0000, v38
	v_cndmask_b32_e32 v16, v16, v17, vcc
	v_sqrt_f32_e32 v17, v16
	v_lshlrev_b32_e32 v26, 16, v39
	v_and_b32_e32 v27, 0xffff0000, v39
	v_lshlrev_b32_e32 v38, 16, v36
	v_add_u32_e32 v18, -1, v17
	v_fma_f32 v19, -v18, v17, v16
	v_cmp_ge_f32_e64 s[0:1], 0, v19
	v_add_u32_e32 v19, 1, v17
	v_and_b32_e32 v39, 0xffff0000, v36
	v_cndmask_b32_e64 v18, v17, v18, s[0:1]
	v_fma_f32 v17, -v19, v17, v16
	v_cmp_lt_f32_e64 s[0:1], 0, v17
	v_lshlrev_b32_e32 v36, 16, v37
	v_and_b32_e32 v37, 0xffff0000, v37
	v_cndmask_b32_e64 v17, v18, v19, s[0:1]
	v_mul_f32_e32 v18, 0x37800000, v17
	v_cndmask_b32_e32 v17, v17, v18, vcc
	v_cmp_class_f32_e32 vcc, v16, v59
	v_lshlrev_b32_e32 v40, 16, v34
	v_and_b32_e32 v41, 0xffff0000, v34
	v_cndmask_b32_e32 v16, v17, v16, vcc
	v_div_scale_f32 v17, s[0:1], v16, v16, 1.0
	v_rcp_f32_e32 v18, v17
	s_lshl_b64 s[0:1], s[4:5], 12
	v_lshl_add_u64 v[42:43], v[32:33], 0, s[0:1]
	v_lshlrev_b32_e32 v34, 16, v35
	v_fma_f32 v19, -v17, v18, 1.0
	v_fmac_f32_e32 v18, v19, v18
	v_div_scale_f32 v19, vcc, 1.0, v16, 1.0
	v_mul_f32_e32 v44, v19, v18
	v_fma_f32 v45, -v17, v44, v19
	v_fmac_f32_e32 v44, v45, v18
	v_fma_f32 v17, -v17, v44, v19
	v_div_fmas_f32 v17, v17, v18, v44
	v_div_fixup_f32 v44, v17, v16, 1.0
	v_pk_mul_f32 v[16:17], v[44:45], v[20:21] op_sel_hi:[0,1]
	v_pk_mul_f32 v[18:19], v[44:45], v[22:23] op_sel_hi:[0,1]
	v_pk_mul_f32 v[18:19], v[2:3], v[18:19]
	v_pk_mul_f32 v[16:17], v[0:1], v[16:17]
	global_store_dwordx4 v[42:43], v[16:19], off nt
	v_and_b32_e32 v35, 0xffff0000, v35
	s_nop 0
	v_pk_mul_f32 v[16:17], v[44:45], v[24:25] op_sel_hi:[0,1]
	v_pk_mul_f32 v[18:19], v[44:45], v[26:27] op_sel_hi:[0,1]
	v_pk_mul_f32 v[18:19], v[6:7], v[18:19]
	v_pk_mul_f32 v[16:17], v[4:5], v[16:17]
	global_store_dwordx4 v[42:43], v[16:19], off offset:1024 nt
	s_nop 1
	v_pk_mul_f32 v[16:17], v[44:45], v[38:39] op_sel_hi:[0,1]
	v_pk_mul_f32 v[18:19], v[44:45], v[36:37] op_sel_hi:[0,1]
	v_pk_mul_f32 v[18:19], v[10:11], v[18:19]
	v_pk_mul_f32 v[16:17], v[8:9], v[16:17]
	global_store_dwordx4 v[42:43], v[16:19], off offset:2048 nt
	s_nop 1
	v_pk_mul_f32 v[16:17], v[44:45], v[40:41] op_sel_hi:[0,1]
	v_pk_mul_f32 v[18:19], v[44:45], v[34:35] op_sel_hi:[0,1]
	v_pk_mul_f32 v[18:19], v[14:15], v[18:19]
	v_pk_mul_f32 v[16:17], v[12:13], v[16:17]
	global_store_dwordx4 v[42:43], v[16:19], off offset:3072 nt
	s_branch .LBB0_2531
